# all 5 GEMM K-loops: LDS-DMA addresses as SGPR base + 32-bit offset (no 64-bit VALU adds in the loop)
# speedup vs baseline: 1.0103x; 1.0007x over previous
; #define PG8_STAGE(bufoff, gbase, voff) do { _Pragma("unroll") for (int _i = 0; _i < 2; ++_i) \
;         __builtin_amdgcn_global_load_lds((const unsigned*)((const char*)(gbase) + (voff)[_i]), (PG8_LAS unsigned*)(lds + (bufoff) + ldsw + _i * 8192), 16, 0, 0); } while (0)
; #define PG8_LDA(dst, b, h) do { _Pragma("unroll") for (int m = 0; m < 4; ++m) _Pragma("unroll") for (int k = 0; k < 2; ++k) dst[m][k] = *(const PG8_LAS bf16x8*)(lds + PG8_SA(b, h) + aoff + m * 2048 + k * 1024); } while (0)
; #define PG8_LDB(dst, b, h) do { _Pragma("unroll") for (int n = 0; n < 2; ++n) _Pragma("unroll") for (int k = 0; k < 2; ++k) dst[n][k] = *(const PG8_LAS bf16x8*)(lds + PG8_SB(b, h) + boff + n * 2048 + k * 1024); } while (0)
; #define PG8_MMA(ai, bj, At, Bt) do { __builtin_amdgcn_s_setprio(1); _Pragma("unroll") for (int m = 0; m < 4; ++m) _Pragma("unroll") for (int n = 0; n < 2; ++n) _Pragma("unroll") for (int k = 0; k < 2; ++k) \
;         acc[ai][bj][m][n] = __builtin_amdgcn_mfma_f32_16x16x32_bf16(Bt[n][k], At[m][k], acc[ai][bj][m][n], 0, 0, 0); __builtin_amdgcn_s_setprio(0); } while (0)
; #define PG8_WAIT_V(n) asm volatile("s_waitcnt vmcnt(" #n ")" ::: "memory")
; #define PG8_WAIT_L(n) asm volatile("s_waitcnt lgkmcnt(" #n ")" ::: "memory")
; #define PG8_BAR __builtin_amdgcn_s_barrier()
; template <class Epi, class Sched, bool ALIGN_EPI = true>
; __device__ __forceinline__ void gemm_phase(PG8_LAS unsigned char* lds, const Gemm g, const Sched& S, const Epi& E, const int tid) {
;     ...
;             const bool last = (t == nt - 2);
;             const char* a1 = cA + (size_t)(t + 1) * kstep;
;             const char* a2 = last ? nA : cA + (size_t)(t + 2) * kstep; const char* b2 = last ? nB : cB + (size_t)(t + 2) * kstep;
;             const char* a3 = a2 + kstep; const char* b3 = b2 + kstep;
;             if (last && has_next) S.a_ready(nxt);
;             PG8_LDB(B0, 0, 0); PG8_LDB(B1, 0, 1); PG8_SCHED; PG8_LDA(At, 0, 0); PG8_STAGE(PG8_SA(1, 1), a1 + hstepA, voffA);
;             PG8_WAIT_V(8); PG8_WAIT_L(0); PG8_BAR; PG8_MMA(0, 0, At, B0); PG8_MMA(0, 1, At, B1); PG8_BAR; PG8_SCHED;
;             PG8_LDA(At, 0, 1); PG8_STAGE(PG8_SB(0, 0), b2, voffB); PG8_STAGE(PG8_SB(0, 1), b2 + hstepB, voffB); PG8_STAGE(PG8_SA(0, 0), a2, voffA);
;             PG8_WAIT_V(8); PG8_WAIT_L(0); PG8_BAR; PG8_MMA(1, 0, At, B0); PG8_MMA(1, 1, At, B1); PG8_BAR; PG8_SCHED;
.LBB0_426:
	s_add_u32 s15, s12, 0xfff80080
	s_addc_u32 s16, s13, -1
	s_add_i32 s17, 0, 0x10000
	s_cmp_eq_u32 s53, 4
	s_cselect_b32 s63, s1, s16
	s_cselect_b32 s62, s5, s15
	s_cselect_b32 s23, s8, s21
	s_cselect_b32 s22, s9, s20
	s_add_i32 s15, 0, 0x14000
	v_add_u32_e32 v72, s17, v251
	v_add_u32_e32 v136, s15, v251
	ds_read_b128 v[60:63], v72
	ds_read_b128 v[64:67], v72 offset:1024
	ds_read_b128 v[68:71], v72 offset:2048
	ds_read_b128 v[72:75], v72 offset:3072
	ds_read_b128 v[100:103], v136
	ds_read_b128 v[112:115], v136 offset:1024
	ds_read_b128 v[116:119], v136 offset:2048
	ds_read_b128 v[136:139], v136 offset:3072
	s_add_i32 m0, s11, 0xc000
	ds_read_b128 v[140:143], v252
	ds_read_b128 v[152:155], v252 offset:1024
	ds_read_b128 v[156:159], v252 offset:2048
	ds_read_b128 v[168:171], v252 offset:3072
	ds_read_b128 v[172:175], v252 offset:4096
	ds_read_b128 v[184:187], v252 offset:5120
	ds_read_b128 v[188:191], v252 offset:6144
	ds_read_b128 v[192:195], v252 offset:7168
	global_load_lds_dwordx4 v216, s[12:13]
	s_add_i32 m0, s11, 0xe000
	s_nop 0
	global_load_lds_dwordx4 v218, s[12:13]
	s_waitcnt vmcnt(8)
	s_waitcnt lgkmcnt(0)
	s_barrier
	s_waitcnt lgkmcnt(0)
	v_mfma_f32_16x16x32_bf16 v[180:183], v[60:63], v[140:143], v[180:183]
	v_mfma_f32_16x16x32_bf16 v[180:183], v[64:67], v[152:155], v[180:183]
	v_mfma_f32_16x16x32_bf16 v[176:179], v[68:71], v[140:143], v[176:179]
	v_mfma_f32_16x16x32_bf16 v[176:179], v[72:75], v[152:155], v[176:179]
	v_mfma_f32_16x16x32_bf16 v[148:151], v[60:63], v[156:159], v[148:151]
	v_mfma_f32_16x16x32_bf16 v[148:151], v[64:67], v[168:171], v[148:151]
	v_mfma_f32_16x16x32_bf16 v[144:147], v[68:71], v[156:159], v[144:147]
	v_mfma_f32_16x16x32_bf16 v[144:147], v[72:75], v[168:171], v[144:147]
	v_mfma_f32_16x16x32_bf16 v[124:127], v[60:63], v[172:175], v[124:127]
	v_mfma_f32_16x16x32_bf16 v[124:127], v[64:67], v[184:187], v[124:127]
	v_mfma_f32_16x16x32_bf16 v[120:123], v[68:71], v[172:175], v[120:123]
	v_mfma_f32_16x16x32_bf16 v[120:123], v[72:75], v[184:187], v[120:123]
	v_mfma_f32_16x16x32_bf16 v[96:99], v[60:63], v[188:191], v[96:99]
	v_mfma_f32_16x16x32_bf16 v[96:99], v[64:67], v[192:195], v[96:99]
	v_mfma_f32_16x16x32_bf16 v[92:95], v[68:71], v[188:191], v[92:95]
	v_mfma_f32_16x16x32_bf16 v[92:95], v[72:75], v[192:195], v[92:95]
	v_mfma_f32_16x16x32_bf16 v[164:167], v[100:103], v[140:143], v[164:167]
	v_mfma_f32_16x16x32_bf16 v[132:135], v[100:103], v[156:159], v[132:135]
	v_mfma_f32_16x16x32_bf16 v[128:131], v[116:119], v[156:159], v[128:131]
	v_mfma_f32_16x16x32_bf16 v[108:111], v[100:103], v[172:175], v[108:111]
	v_mfma_f32_16x16x32_bf16 v[104:107], v[116:119], v[172:175], v[104:107]
	v_mfma_f32_16x16x32_bf16 v[88:91], v[100:103], v[188:191], v[88:91]
	v_mfma_f32_16x16x32_bf16 v[84:87], v[116:119], v[188:191], v[84:87]
	v_mfma_f32_16x16x32_bf16 v[164:167], v[112:115], v[152:155], v[164:167]
	v_mfma_f32_16x16x32_bf16 v[140:143], v[116:119], v[140:143], v[160:163]
	v_mfma_f32_16x16x32_bf16 v[132:135], v[112:115], v[168:171], v[132:135]
	v_mfma_f32_16x16x32_bf16 v[128:131], v[136:139], v[168:171], v[128:131]
	v_mfma_f32_16x16x32_bf16 v[108:111], v[112:115], v[184:187], v[108:111]
	v_mfma_f32_16x16x32_bf16 v[104:107], v[136:139], v[184:187], v[104:107]
	v_mfma_f32_16x16x32_bf16 v[88:91], v[112:115], v[192:195], v[88:91]
	v_mfma_f32_16x16x32_bf16 v[84:87], v[136:139], v[192:195], v[84:87]
	v_mfma_f32_16x16x32_bf16 v[140:143], v[136:139], v[152:155], v[140:143]
	s_barrier
	s_add_i32 s16, s17, s67
	s_mov_b32 m0, s16
	ds_read_b128 v[152:155], v252 offset:16384
	ds_read_b128 v[156:159], v252 offset:17408
	ds_read_b128 v[160:163], v252 offset:18432
	ds_read_b128 v[168:171], v252 offset:19456
	ds_read_b128 v[172:175], v252 offset:20480
	ds_read_b128 v[184:187], v252 offset:21504
	ds_read_b128 v[188:191], v252 offset:22528
	ds_read_b128 v[192:195], v252 offset:23552
	global_load_lds_dwordx4 v2, s[22:23]
	s_add_i32 m0, s16, 0x2000
	s_add_u32 s78, s22, 0x20000
	s_addc_u32 s79, s23, 0
	s_add_i32 s15, s15, s67
	global_load_lds_dwordx4 v210, s[22:23]
	s_mov_b32 m0, s15
	s_nop 0
	global_load_lds_dwordx4 v2, s[78:79]
	s_add_i32 m0, s15, 0x2000
	s_nop 0
	global_load_lds_dwordx4 v210, s[78:79]
	s_mov_b32 m0, s11
	s_nop 0
	global_load_lds_dwordx4 v214, s[62:63]
	s_mov_b32 m0, s68
	s_nop 0
	global_load_lds_dwordx4 v212, s[62:63]
	s_waitcnt vmcnt(8)
	s_waitcnt lgkmcnt(0)
	s_barrier
	s_waitcnt lgkmcnt(0)
	v_mfma_f32_16x16x32_bf16 v[80:83], v[60:63], v[152:155], v[80:83]
	v_mfma_f32_16x16x32_bf16 v[80:83], v[64:67], v[156:159], v[80:83]
	v_mfma_f32_16x16x32_bf16 v[76:79], v[68:71], v[152:155], v[76:79]
	v_mfma_f32_16x16x32_bf16 v[76:79], v[72:75], v[156:159], v[76:79]
	v_mfma_f32_16x16x32_bf16 v[48:51], v[60:63], v[160:163], v[48:51]
	v_mfma_f32_16x16x32_bf16 v[48:51], v[64:67], v[168:171], v[48:51]
	v_mfma_f32_16x16x32_bf16 v[44:47], v[68:71], v[160:163], v[44:47]
	v_mfma_f32_16x16x32_bf16 v[44:47], v[72:75], v[168:171], v[44:47]
	v_mfma_f32_16x16x32_bf16 v[32:35], v[60:63], v[172:175], v[32:35]
	v_mfma_f32_16x16x32_bf16 v[32:35], v[64:67], v[184:187], v[32:35]
	v_mfma_f32_16x16x32_bf16 v[28:31], v[68:71], v[172:175], v[28:31]
	v_mfma_f32_16x16x32_bf16 v[28:31], v[72:75], v[184:187], v[28:31]
	v_mfma_f32_16x16x32_bf16 v[16:19], v[60:63], v[188:191], v[16:19]
	v_mfma_f32_16x16x32_bf16 v[16:19], v[64:67], v[192:195], v[16:19]
	v_mfma_f32_16x16x32_bf16 v[12:15], v[68:71], v[188:191], v[12:15]
	v_mfma_f32_16x16x32_bf16 v[12:15], v[72:75], v[192:195], v[12:15]
	v_mfma_f32_16x16x32_bf16 v[56:59], v[100:103], v[152:155], v[56:59]
	v_mfma_f32_16x16x32_bf16 v[56:59], v[112:115], v[156:159], v[56:59]
	v_mfma_f32_16x16x32_bf16 v[52:55], v[116:119], v[152:155], v[52:55]
	v_mfma_f32_16x16x32_bf16 v[52:55], v[136:139], v[156:159], v[52:55]
	v_mfma_f32_16x16x32_bf16 v[40:43], v[100:103], v[160:163], v[40:43]
	v_mfma_f32_16x16x32_bf16 v[40:43], v[112:115], v[168:171], v[40:43]
	v_mfma_f32_16x16x32_bf16 v[36:39], v[116:119], v[160:163], v[36:39]
	v_mfma_f32_16x16x32_bf16 v[36:39], v[136:139], v[168:171], v[36:39]
	v_mfma_f32_16x16x32_bf16 v[24:27], v[100:103], v[172:175], v[24:27]
	v_mfma_f32_16x16x32_bf16 v[24:27], v[112:115], v[184:187], v[24:27]
	v_mfma_f32_16x16x32_bf16 v[20:23], v[116:119], v[172:175], v[20:23]
	v_mfma_f32_16x16x32_bf16 v[20:23], v[136:139], v[184:187], v[20:23]
	v_mfma_f32_16x16x32_bf16 v[8:11], v[100:103], v[188:191], v[8:11]
	v_mfma_f32_16x16x32_bf16 v[8:11], v[112:115], v[192:195], v[8:11]
	v_mfma_f32_16x16x32_bf16 v[4:7], v[116:119], v[188:191], v[4:7]
	v_mfma_f32_16x16x32_bf16 v[4:7], v[136:139], v[192:195], v[4:7]
	s_barrier
; #define PG8_STAGE(bufoff, gbase, voff) do { _Pragma("unroll") for (int _i = 0; _i < 2; ++_i) \
;         __builtin_amdgcn_global_load_lds((const unsigned*)((const char*)(gbase) + (voff)[_i]), (PG8_LAS unsigned*)(lds + (bufoff) + ldsw + _i * 8192), 16, 0, 0); } while (0)
; #define PG8_LDA(dst, b, h) do { _Pragma("unroll") for (int m = 0; m < 4; ++m) _Pragma("unroll") for (int k = 0; k < 2; ++k) dst[m][k] = *(const PG8_LAS bf16x8*)(lds + PG8_SA(b, h) + aoff + m * 2048 + k * 1024); } while (0)
; #define PG8_LDB(dst, b, h) do { _Pragma("unroll") for (int n = 0; n < 2; ++n) _Pragma("unroll") for (int k = 0; k < 2; ++k) dst[n][k] = *(const PG8_LAS bf16x8*)(lds + PG8_SB(b, h) + boff + n * 2048 + k * 1024); } while (0)
; #define PG8_MMA(ai, bj, At, Bt) do { __builtin_amdgcn_s_setprio(1); _Pragma("unroll") for (int m = 0; m < 4; ++m) _Pragma("unroll") for (int n = 0; n < 2; ++n) _Pragma("unroll") for (int k = 0; k < 2; ++k) \
;         acc[ai][bj][m][n] = __builtin_amdgcn_mfma_f32_16x16x32_bf16(Bt[n][k], At[m][k], acc[ai][bj][m][n], 0, 0, 0); __builtin_amdgcn_s_setprio(0); } while (0)
; #define PG8_WAIT_V(n) asm volatile("s_waitcnt vmcnt(" #n ")" ::: "memory")
; #define PG8_WAIT_L(n) asm volatile("s_waitcnt lgkmcnt(" #n ")" ::: "memory")
; #define PG8_BAR __builtin_amdgcn_s_barrier()
; #define PG8_SCHED __builtin_amdgcn_sched_barrier(0)
; template <class Epi, class Sched, bool ALIGN_EPI = true>
; __device__ __forceinline__ void gemm_phase(PG8_LAS unsigned char* lds, const Gemm g, const Sched& S, const Epi& E, const int tid) {
;     ...
;             PG8_LDB(B0, 1, 0); PG8_LDB(B1, 1, 1); PG8_SCHED; PG8_LDA(At, 1, 0); PG8_STAGE(PG8_SA(0, 1), a2 + hstepA, voffA);
;             PG8_WAIT_V(8); PG8_WAIT_L(0); PG8_BAR; PG8_MMA(0, 0, At, B0); PG8_MMA(0, 1, At, B1); PG8_BAR; PG8_SCHED;
;             PG8_LDA(At, 1, 1); PG8_STAGE(PG8_SB(1, 0), b3, voffB); PG8_STAGE(PG8_SB(1, 1), b3 + hstepB, voffB); PG8_STAGE(PG8_SA(1, 0), a3, voffA);
;             PG8_WAIT_V(8); PG8_WAIT_L(0); PG8_BAR; PG8_MMA(1, 0, At, B0); PG8_MMA(1, 1, At, B1); PG8_BAR; PG8_SCHED;
;         }
;         if constexpr (ALIGN_EPI) { if (wr == 0) PG8_BAR; }
;         E(acc, cur, wr, wc, fr, fq); S.done(cur);
;         if (!has_next) break;
	s_add_i32 s15, 0, 0x18000
	s_add_i32 s16, 0, 0x1c000
	v_add_u32_e32 v72, s15, v251
	v_add_u32_e32 v136, s16, v251
	ds_read_b128 v[60:63], v72
	ds_read_b128 v[64:67], v72 offset:1024
	ds_read_b128 v[68:71], v72 offset:2048
	ds_read_b128 v[72:75], v72 offset:3072
	ds_read_b128 v[100:103], v136
	ds_read_b128 v[112:115], v136 offset:1024
	ds_read_b128 v[116:119], v136 offset:2048
	ds_read_b128 v[136:139], v136 offset:3072
	s_add_u32 s62, s62, 0x80000
	s_addc_u32 s63, s63, 0
	s_mov_b32 m0, s69
	ds_read_b128 v[152:155], v252 offset:32768
	ds_read_b128 v[156:159], v252 offset:33792
	ds_read_b128 v[168:171], v252 offset:34816
	ds_read_b128 v[172:175], v252 offset:35840
	ds_read_b128 v[184:187], v252 offset:36864
	ds_read_b128 v[188:191], v252 offset:37888
	ds_read_b128 v[192:195], v252 offset:38912
	ds_read_b128 v[196:199], v252 offset:39936
	global_load_lds_dwordx4 v214, s[62:63]
	s_mov_b32 m0, s70
	s_nop 0
	global_load_lds_dwordx4 v212, s[62:63]
	s_waitcnt vmcnt(8)
	s_waitcnt lgkmcnt(0)
	s_barrier
	s_waitcnt lgkmcnt(0)
	v_mfma_f32_16x16x32_bf16 v[160:163], v[60:63], v[152:155], v[180:183]
	v_mfma_f32_16x16x32_bf16 v[180:183], v[64:67], v[156:159], v[160:163]
	v_mfma_f32_16x16x32_bf16 v[160:163], v[68:71], v[152:155], v[176:179]
	v_mfma_f32_16x16x32_bf16 v[148:151], v[60:63], v[168:171], v[148:151]
	v_mfma_f32_16x16x32_bf16 v[144:147], v[68:71], v[168:171], v[144:147]
	v_mfma_f32_16x16x32_bf16 v[124:127], v[60:63], v[184:187], v[124:127]
	v_mfma_f32_16x16x32_bf16 v[120:123], v[68:71], v[184:187], v[120:123]
	v_mfma_f32_16x16x32_bf16 v[96:99], v[60:63], v[192:195], v[96:99]
	v_mfma_f32_16x16x32_bf16 v[92:95], v[68:71], v[192:195], v[92:95]
	v_mfma_f32_16x16x32_bf16 v[176:179], v[72:75], v[156:159], v[160:163]
	v_mfma_f32_16x16x32_bf16 v[148:151], v[64:67], v[172:175], v[148:151]
	v_mfma_f32_16x16x32_bf16 v[144:147], v[72:75], v[172:175], v[144:147]
	v_mfma_f32_16x16x32_bf16 v[124:127], v[64:67], v[188:191], v[124:127]
	v_mfma_f32_16x16x32_bf16 v[120:123], v[72:75], v[188:191], v[120:123]
	v_mfma_f32_16x16x32_bf16 v[96:99], v[64:67], v[196:199], v[96:99]
	v_mfma_f32_16x16x32_bf16 v[92:95], v[72:75], v[196:199], v[92:95]
	v_mfma_f32_16x16x32_bf16 v[160:163], v[100:103], v[152:155], v[164:167]
	v_mfma_f32_16x16x32_bf16 v[140:143], v[116:119], v[152:155], v[140:143]
	v_mfma_f32_16x16x32_bf16 v[132:135], v[100:103], v[168:171], v[132:135]
	v_mfma_f32_16x16x32_bf16 v[128:131], v[116:119], v[168:171], v[128:131]
	v_mfma_f32_16x16x32_bf16 v[108:111], v[100:103], v[184:187], v[108:111]
	v_mfma_f32_16x16x32_bf16 v[104:107], v[116:119], v[184:187], v[104:107]
	v_mfma_f32_16x16x32_bf16 v[88:91], v[100:103], v[192:195], v[88:91]
	v_mfma_f32_16x16x32_bf16 v[84:87], v[116:119], v[192:195], v[84:87]
	v_mfma_f32_16x16x32_bf16 v[164:167], v[112:115], v[156:159], v[160:163]
	v_mfma_f32_16x16x32_bf16 v[160:163], v[136:139], v[156:159], v[140:143]
	v_mfma_f32_16x16x32_bf16 v[132:135], v[112:115], v[172:175], v[132:135]
	v_mfma_f32_16x16x32_bf16 v[128:131], v[136:139], v[172:175], v[128:131]
	v_mfma_f32_16x16x32_bf16 v[108:111], v[112:115], v[188:191], v[108:111]
	v_mfma_f32_16x16x32_bf16 v[104:107], v[136:139], v[188:191], v[104:107]
	v_mfma_f32_16x16x32_bf16 v[88:91], v[112:115], v[196:199], v[88:91]
	v_mfma_f32_16x16x32_bf16 v[84:87], v[136:139], v[196:199], v[84:87]
	s_barrier
	s_add_i32 s15, s15, s67
	s_mov_b32 m0, s15
	ds_read_b128 v[140:143], v252 offset:49152
	ds_read_b128 v[152:155], v252 offset:50176
	ds_read_b128 v[156:159], v252 offset:51200
	ds_read_b128 v[168:171], v252 offset:52224
	ds_read_b128 v[172:175], v252 offset:53248
	ds_read_b128 v[184:187], v252 offset:54272
	ds_read_b128 v[188:191], v252 offset:55296
	ds_read_b128 v[192:195], v252 offset:56320
	s_add_u32 s98, s22, 0x80
	s_addc_u32 s99, s23, 0
	global_load_lds_dwordx4 v2, s[98:99]
	s_add_i32 m0, s15, 0x2000
	s_add_u32 s22, s22, 0x20080
	s_addc_u32 s23, s23, 0
	s_add_i32 s15, s16, s67
	global_load_lds_dwordx4 v210, s[98:99]
	s_mov_b32 m0, s15
	s_nop 0
	global_load_lds_dwordx4 v2, s[22:23]
	s_add_i32 m0, s15, 0x2000
	s_nop 0
	global_load_lds_dwordx4 v210, s[22:23]
	s_mov_b32 m0, s75
	s_nop 0
	s_add_u32 s98, s62, 0xfff80080
	s_addc_u32 s99, s63, -1
	global_load_lds_dwordx4 v214, s[98:99]
	s_mov_b32 m0, s76
	s_nop 0
	global_load_lds_dwordx4 v212, s[98:99]
	s_waitcnt vmcnt(8)
	s_waitcnt lgkmcnt(0)
	s_barrier
	s_waitcnt lgkmcnt(0)
	v_mfma_f32_16x16x32_bf16 v[80:83], v[60:63], v[140:143], v[80:83]
	v_mfma_f32_16x16x32_bf16 v[80:83], v[64:67], v[152:155], v[80:83]
	v_mfma_f32_16x16x32_bf16 v[76:79], v[68:71], v[140:143], v[76:79]
	v_mfma_f32_16x16x32_bf16 v[76:79], v[72:75], v[152:155], v[76:79]
	v_mfma_f32_16x16x32_bf16 v[48:51], v[60:63], v[156:159], v[48:51]
	v_mfma_f32_16x16x32_bf16 v[48:51], v[64:67], v[168:171], v[48:51]
	v_mfma_f32_16x16x32_bf16 v[44:47], v[68:71], v[156:159], v[44:47]
	v_mfma_f32_16x16x32_bf16 v[44:47], v[72:75], v[168:171], v[44:47]
	v_mfma_f32_16x16x32_bf16 v[32:35], v[60:63], v[172:175], v[32:35]
	v_mfma_f32_16x16x32_bf16 v[32:35], v[64:67], v[184:187], v[32:35]
	v_mfma_f32_16x16x32_bf16 v[28:31], v[68:71], v[172:175], v[28:31]
	v_mfma_f32_16x16x32_bf16 v[28:31], v[72:75], v[184:187], v[28:31]
	v_mfma_f32_16x16x32_bf16 v[16:19], v[60:63], v[188:191], v[16:19]
	v_mfma_f32_16x16x32_bf16 v[16:19], v[64:67], v[192:195], v[16:19]
	v_mfma_f32_16x16x32_bf16 v[12:15], v[68:71], v[188:191], v[12:15]
	v_mfma_f32_16x16x32_bf16 v[12:15], v[72:75], v[192:195], v[12:15]
	v_mfma_f32_16x16x32_bf16 v[56:59], v[100:103], v[140:143], v[56:59]
	v_mfma_f32_16x16x32_bf16 v[56:59], v[112:115], v[152:155], v[56:59]
	v_mfma_f32_16x16x32_bf16 v[52:55], v[116:119], v[140:143], v[52:55]
	v_mfma_f32_16x16x32_bf16 v[52:55], v[136:139], v[152:155], v[52:55]
	v_mfma_f32_16x16x32_bf16 v[40:43], v[100:103], v[156:159], v[40:43]
	v_mfma_f32_16x16x32_bf16 v[40:43], v[112:115], v[168:171], v[40:43]
	v_mfma_f32_16x16x32_bf16 v[36:39], v[116:119], v[156:159], v[36:39]
	v_mfma_f32_16x16x32_bf16 v[36:39], v[136:139], v[168:171], v[36:39]
	v_mfma_f32_16x16x32_bf16 v[24:27], v[100:103], v[172:175], v[24:27]
	v_mfma_f32_16x16x32_bf16 v[24:27], v[112:115], v[184:187], v[24:27]
	v_mfma_f32_16x16x32_bf16 v[20:23], v[116:119], v[172:175], v[20:23]
	v_mfma_f32_16x16x32_bf16 v[20:23], v[136:139], v[184:187], v[20:23]
	v_mfma_f32_16x16x32_bf16 v[8:11], v[100:103], v[188:191], v[8:11]
	v_mfma_f32_16x16x32_bf16 v[8:11], v[112:115], v[192:195], v[8:11]
	v_mfma_f32_16x16x32_bf16 v[4:7], v[116:119], v[188:191], v[4:7]
	v_mfma_f32_16x16x32_bf16 v[4:7], v[136:139], v[192:195], v[4:7]
	s_barrier
	s_add_i32 s53, s53, 2
	s_add_u32 s12, s12, 0x100
	s_addc_u32 s13, s13, 0
	s_add_u32 s20, s20, 0x100
	s_addc_u32 s21, s21, 0
	s_cmp_gt_u32 s53, 5
	s_cbranch_scc0 .LBB0_426
	s_and_b64 vcc, exec, s[48:49]
	s_cbranch_vccz .LBB0_429
	s_barrier

; #define PG8_STAGE(bufoff, gbase, voff) do { _Pragma("unroll") for (int _i = 0; _i < 2; ++_i) \
;         __builtin_amdgcn_global_load_lds((const unsigned*)((const char*)(gbase) + (voff)[_i]), (PG8_LAS unsigned*)(lds + (bufoff) + ldsw + _i * 8192), 16, 0, 0); } while (0)
; #define PG8_LDA(dst, b, h) do { _Pragma("unroll") for (int m = 0; m < 4; ++m) _Pragma("unroll") for (int k = 0; k < 2; ++k) dst[m][k] = *(const PG8_LAS bf16x8*)(lds + PG8_SA(b, h) + aoff + m * 2048 + k * 1024); } while (0)
; #define PG8_LDB(dst, b, h) do { _Pragma("unroll") for (int n = 0; n < 2; ++n) _Pragma("unroll") for (int k = 0; k < 2; ++k) dst[n][k] = *(const PG8_LAS bf16x8*)(lds + PG8_SB(b, h) + boff + n * 2048 + k * 1024); } while (0)
; #define PG8_MMA(ai, bj, At, Bt) do { __builtin_amdgcn_s_setprio(1); _Pragma("unroll") for (int m = 0; m < 4; ++m) _Pragma("unroll") for (int n = 0; n < 2; ++n) _Pragma("unroll") for (int k = 0; k < 2; ++k) \
;         acc[ai][bj][m][n] = __builtin_amdgcn_mfma_f32_16x16x32_bf16(Bt[n][k], At[m][k], acc[ai][bj][m][n], 0, 0, 0); __builtin_amdgcn_s_setprio(0); } while (0)
; #define PG8_WAIT_V(n) asm volatile("s_waitcnt vmcnt(" #n ")" ::: "memory")
; #define PG8_WAIT_L(n) asm volatile("s_waitcnt lgkmcnt(" #n ")" ::: "memory")
; #define PG8_BAR __builtin_amdgcn_s_barrier()
; template <class Epi, class Sched, bool ALIGN_EPI = true>
; __device__ __forceinline__ void gemm_phase(PG8_LAS unsigned char* lds, const Gemm g, const Sched& S, const Epi& E, const int tid) {
;     ...
;             const bool last = (t == nt - 2);
;             const char* a1 = cA + (size_t)(t + 1) * kstep;
;             const char* a2 = last ? nA : cA + (size_t)(t + 2) * kstep; const char* b2 = last ? nB : cB + (size_t)(t + 2) * kstep;
;             const char* a3 = a2 + kstep; const char* b3 = b2 + kstep;
;             if (last && has_next) S.a_ready(nxt);
;             PG8_LDB(B0, 0, 0); PG8_LDB(B1, 0, 1); PG8_SCHED; PG8_LDA(At, 0, 0); PG8_STAGE(PG8_SA(1, 1), a1 + hstepA, voffA);
;             PG8_WAIT_V(8); PG8_WAIT_L(0); PG8_BAR; PG8_MMA(0, 0, At, B0); PG8_MMA(0, 1, At, B1); PG8_BAR; PG8_SCHED;
;             PG8_LDA(At, 0, 1); PG8_STAGE(PG8_SB(0, 0), b2, voffB); PG8_STAGE(PG8_SB(0, 1), b2 + hstepB, voffB); PG8_STAGE(PG8_SA(0, 0), a2, voffA);
;             PG8_WAIT_V(8); PG8_WAIT_L(0); PG8_BAR; PG8_MMA(1, 0, At, B0); PG8_MMA(1, 1, At, B1); PG8_BAR; PG8_SCHED;
.LBB0_514:
	s_add_u32 s44, s42, 0xfff80080
	s_addc_u32 s45, s43, -1
	s_add_i32 s57, 0, 0x10000
	s_cmp_eq_u32 s56, 28
	s_cselect_b32 s47, s13, s45
	s_cselect_b32 s46, s52, s44
	s_cselect_b32 s45, s23, s55
	s_cselect_b32 s44, s53, s54
	s_add_i32 s60, 0, 0x14000
	v_add_u32_e32 v158, s57, v147
	v_add_u32_e32 v174, s60, v147
	ds_read_b128 v[142:145], v158
	ds_read_b128 v[150:153], v158 offset:1024
	ds_read_b128 v[154:157], v158 offset:2048
	ds_read_b128 v[158:161], v158 offset:3072
	ds_read_b128 v[162:165], v174
	ds_read_b128 v[166:169], v174 offset:1024
	ds_read_b128 v[170:173], v174 offset:2048
	ds_read_b128 v[174:177], v174 offset:3072
	s_add_i32 m0, s7, 0xc000
	ds_read_b128 v[178:181], v149
	ds_read_b128 v[182:185], v149 offset:1024
	ds_read_b128 v[186:189], v149 offset:2048
	ds_read_b128 v[190:193], v149 offset:3072
	ds_read_b128 v[194:197], v149 offset:4096
	ds_read_b128 v[198:201], v149 offset:5120
	ds_read_b128 v[202:205], v149 offset:6144
	ds_read_b128 v[210:213], v149 offset:7168
	global_load_lds_dwordx4 v138, s[42:43]
	s_add_i32 m0, s7, 0xe000
	s_nop 0
	global_load_lds_dwordx4 v140, s[42:43]
	s_waitcnt vmcnt(8)
	s_waitcnt lgkmcnt(0)
	s_barrier
	s_waitcnt lgkmcnt(0)
	v_mfma_f32_16x16x32_bf16 v[128:131], v[142:145], v[178:181], v[128:131]
	v_mfma_f32_16x16x32_bf16 v[128:131], v[150:153], v[182:185], v[128:131]
	v_mfma_f32_16x16x32_bf16 v[124:127], v[154:157], v[178:181], v[124:127]
	v_mfma_f32_16x16x32_bf16 v[124:127], v[158:161], v[182:185], v[124:127]
	v_mfma_f32_16x16x32_bf16 v[120:123], v[142:145], v[186:189], v[120:123]
	v_mfma_f32_16x16x32_bf16 v[120:123], v[150:153], v[190:193], v[120:123]
	v_mfma_f32_16x16x32_bf16 v[112:115], v[154:157], v[186:189], v[112:115]
	v_mfma_f32_16x16x32_bf16 v[112:115], v[158:161], v[190:193], v[112:115]
	v_mfma_f32_16x16x32_bf16 v[104:107], v[142:145], v[194:197], v[104:107]
	v_mfma_f32_16x16x32_bf16 v[104:107], v[150:153], v[198:201], v[104:107]
	v_mfma_f32_16x16x32_bf16 v[96:99], v[154:157], v[194:197], v[96:99]
	v_mfma_f32_16x16x32_bf16 v[96:99], v[158:161], v[198:201], v[96:99]
	v_mfma_f32_16x16x32_bf16 v[88:91], v[142:145], v[202:205], v[88:91]
	v_mfma_f32_16x16x32_bf16 v[88:91], v[150:153], v[210:213], v[88:91]
	v_mfma_f32_16x16x32_bf16 v[80:83], v[154:157], v[202:205], v[80:83]
	v_mfma_f32_16x16x32_bf16 v[80:83], v[158:161], v[210:213], v[80:83]
	v_mfma_f32_16x16x32_bf16 v[116:119], v[162:165], v[178:181], v[116:119]
	v_mfma_f32_16x16x32_bf16 v[116:119], v[166:169], v[182:185], v[116:119]
	v_mfma_f32_16x16x32_bf16 v[108:111], v[170:173], v[178:181], v[108:111]
	v_mfma_f32_16x16x32_bf16 v[108:111], v[174:177], v[182:185], v[108:111]
	v_mfma_f32_16x16x32_bf16 v[100:103], v[162:165], v[186:189], v[100:103]
	v_mfma_f32_16x16x32_bf16 v[100:103], v[166:169], v[190:193], v[100:103]
	v_mfma_f32_16x16x32_bf16 v[92:95], v[170:173], v[186:189], v[92:95]
	v_mfma_f32_16x16x32_bf16 v[92:95], v[174:177], v[190:193], v[92:95]
	v_mfma_f32_16x16x32_bf16 v[84:87], v[162:165], v[194:197], v[84:87]
	v_mfma_f32_16x16x32_bf16 v[84:87], v[166:169], v[198:201], v[84:87]
	v_mfma_f32_16x16x32_bf16 v[76:79], v[170:173], v[194:197], v[76:79]
	v_mfma_f32_16x16x32_bf16 v[76:79], v[174:177], v[198:201], v[76:79]
	v_mfma_f32_16x16x32_bf16 v[72:75], v[162:165], v[202:205], v[72:75]
	v_mfma_f32_16x16x32_bf16 v[72:75], v[166:169], v[210:213], v[72:75]
	v_mfma_f32_16x16x32_bf16 v[68:71], v[170:173], v[202:205], v[68:71]
	v_mfma_f32_16x16x32_bf16 v[68:71], v[174:177], v[210:213], v[68:71]
	s_barrier
	s_add_i32 s57, s57, s21
	s_mov_b32 m0, s57
	ds_read_b128 v[178:181], v149 offset:16384
	ds_read_b128 v[182:185], v149 offset:17408
	ds_read_b128 v[186:189], v149 offset:18432
	ds_read_b128 v[190:193], v149 offset:19456
	ds_read_b128 v[194:197], v149 offset:20480
	ds_read_b128 v[198:201], v149 offset:21504
	ds_read_b128 v[202:205], v149 offset:22528
	ds_read_b128 v[210:213], v149 offset:23552
	global_load_lds_dwordx4 v2, s[44:45]
	s_add_i32 m0, s57, 0x2000
	s_add_u32 s58, s44, 0x80000
	s_addc_u32 s59, s45, 0
	s_add_i32 s57, s60, s21
	global_load_lds_dwordx4 v132, s[44:45]
	s_mov_b32 m0, s57
	s_nop 0
	global_load_lds_dwordx4 v2, s[58:59]
	s_add_i32 m0, s57, 0x2000
	s_nop 0
	global_load_lds_dwordx4 v132, s[58:59]
	s_mov_b32 m0, s7
	s_nop 0
	global_load_lds_dwordx4 v136, s[46:47]
	s_mov_b32 m0, s11
	s_nop 0
	global_load_lds_dwordx4 v134, s[46:47]
	s_waitcnt vmcnt(8)
	s_waitcnt lgkmcnt(0)
	s_barrier
	s_waitcnt lgkmcnt(0)
	v_mfma_f32_16x16x32_bf16 v[64:67], v[142:145], v[178:181], v[64:67]
	v_mfma_f32_16x16x32_bf16 v[64:67], v[150:153], v[182:185], v[64:67]
	v_mfma_f32_16x16x32_bf16 v[60:63], v[154:157], v[178:181], v[60:63]
	v_mfma_f32_16x16x32_bf16 v[60:63], v[158:161], v[182:185], v[60:63]
	v_mfma_f32_16x16x32_bf16 v[56:59], v[142:145], v[186:189], v[56:59]
	v_mfma_f32_16x16x32_bf16 v[56:59], v[150:153], v[190:193], v[56:59]
	v_mfma_f32_16x16x32_bf16 v[48:51], v[154:157], v[186:189], v[48:51]
	v_mfma_f32_16x16x32_bf16 v[48:51], v[158:161], v[190:193], v[48:51]
	v_mfma_f32_16x16x32_bf16 v[40:43], v[142:145], v[194:197], v[40:43]
	v_mfma_f32_16x16x32_bf16 v[40:43], v[150:153], v[198:201], v[40:43]
	v_mfma_f32_16x16x32_bf16 v[32:35], v[154:157], v[194:197], v[32:35]
	v_mfma_f32_16x16x32_bf16 v[32:35], v[158:161], v[198:201], v[32:35]
	v_mfma_f32_16x16x32_bf16 v[24:27], v[142:145], v[202:205], v[24:27]
	v_mfma_f32_16x16x32_bf16 v[24:27], v[150:153], v[210:213], v[24:27]
	v_mfma_f32_16x16x32_bf16 v[16:19], v[154:157], v[202:205], v[16:19]
	v_mfma_f32_16x16x32_bf16 v[16:19], v[158:161], v[210:213], v[16:19]
	v_mfma_f32_16x16x32_bf16 v[52:55], v[162:165], v[178:181], v[52:55]
	v_mfma_f32_16x16x32_bf16 v[52:55], v[166:169], v[182:185], v[52:55]
	v_mfma_f32_16x16x32_bf16 v[44:47], v[170:173], v[178:181], v[44:47]
	v_mfma_f32_16x16x32_bf16 v[44:47], v[174:177], v[182:185], v[44:47]
	v_mfma_f32_16x16x32_bf16 v[36:39], v[162:165], v[186:189], v[36:39]
	v_mfma_f32_16x16x32_bf16 v[36:39], v[166:169], v[190:193], v[36:39]
	v_mfma_f32_16x16x32_bf16 v[28:31], v[170:173], v[186:189], v[28:31]
	v_mfma_f32_16x16x32_bf16 v[28:31], v[174:177], v[190:193], v[28:31]
	v_mfma_f32_16x16x32_bf16 v[20:23], v[162:165], v[194:197], v[20:23]
	v_mfma_f32_16x16x32_bf16 v[20:23], v[166:169], v[198:201], v[20:23]
	v_mfma_f32_16x16x32_bf16 v[12:15], v[170:173], v[194:197], v[12:15]
	v_mfma_f32_16x16x32_bf16 v[12:15], v[174:177], v[198:201], v[12:15]
	v_mfma_f32_16x16x32_bf16 v[8:11], v[162:165], v[202:205], v[8:11]
	v_mfma_f32_16x16x32_bf16 v[8:11], v[166:169], v[210:213], v[8:11]
	v_mfma_f32_16x16x32_bf16 v[4:7], v[170:173], v[202:205], v[4:7]
	v_mfma_f32_16x16x32_bf16 v[4:7], v[174:177], v[210:213], v[4:7]
	s_barrier
; #define PG8_STAGE(bufoff, gbase, voff) do { _Pragma("unroll") for (int _i = 0; _i < 2; ++_i) \
;         __builtin_amdgcn_global_load_lds((const unsigned*)((const char*)(gbase) + (voff)[_i]), (PG8_LAS unsigned*)(lds + (bufoff) + ldsw + _i * 8192), 16, 0, 0); } while (0)
; #define PG8_LDA(dst, b, h) do { _Pragma("unroll") for (int m = 0; m < 4; ++m) _Pragma("unroll") for (int k = 0; k < 2; ++k) dst[m][k] = *(const PG8_LAS bf16x8*)(lds + PG8_SA(b, h) + aoff + m * 2048 + k * 1024); } while (0)
; #define PG8_LDB(dst, b, h) do { _Pragma("unroll") for (int n = 0; n < 2; ++n) _Pragma("unroll") for (int k = 0; k < 2; ++k) dst[n][k] = *(const PG8_LAS bf16x8*)(lds + PG8_SB(b, h) + boff + n * 2048 + k * 1024); } while (0)
; #define PG8_MMA(ai, bj, At, Bt) do { __builtin_amdgcn_s_setprio(1); _Pragma("unroll") for (int m = 0; m < 4; ++m) _Pragma("unroll") for (int n = 0; n < 2; ++n) _Pragma("unroll") for (int k = 0; k < 2; ++k) \
;         acc[ai][bj][m][n] = __builtin_amdgcn_mfma_f32_16x16x32_bf16(Bt[n][k], At[m][k], acc[ai][bj][m][n], 0, 0, 0); __builtin_amdgcn_s_setprio(0); } while (0)
; #define PG8_WAIT_V(n) asm volatile("s_waitcnt vmcnt(" #n ")" ::: "memory")
; #define PG8_WAIT_L(n) asm volatile("s_waitcnt lgkmcnt(" #n ")" ::: "memory")
; #define PG8_BAR __builtin_amdgcn_s_barrier()
; #define PG8_SCHED __builtin_amdgcn_sched_barrier(0)
; template <class Epi, class Sched, bool ALIGN_EPI = true>
; __device__ __forceinline__ void gemm_phase(PG8_LAS unsigned char* lds, const Gemm g, const Sched& S, const Epi& E, const int tid) {
;     ...
;             PG8_LDB(B0, 1, 0); PG8_LDB(B1, 1, 1); PG8_SCHED; PG8_LDA(At, 1, 0); PG8_STAGE(PG8_SA(0, 1), a2 + hstepA, voffA);
;             PG8_WAIT_V(8); PG8_WAIT_L(0); PG8_BAR; PG8_MMA(0, 0, At, B0); PG8_MMA(0, 1, At, B1); PG8_BAR; PG8_SCHED;
;             PG8_LDA(At, 1, 1); PG8_STAGE(PG8_SB(1, 0), b3, voffB); PG8_STAGE(PG8_SB(1, 1), b3 + hstepB, voffB); PG8_STAGE(PG8_SA(1, 0), a3, voffA);
;             PG8_WAIT_V(8); PG8_WAIT_L(0); PG8_BAR; PG8_MMA(1, 0, At, B0); PG8_MMA(1, 1, At, B1); PG8_BAR; PG8_SCHED;
	s_add_i32 s57, 0, 0x18000
	s_add_i32 s58, 0, 0x1c000
	v_add_u32_e32 v158, s57, v147
	v_add_u32_e32 v174, s58, v147
	ds_read_b128 v[142:145], v158
	ds_read_b128 v[150:153], v158 offset:1024
	ds_read_b128 v[154:157], v158 offset:2048
	ds_read_b128 v[158:161], v158 offset:3072
	ds_read_b128 v[162:165], v174
	ds_read_b128 v[166:169], v174 offset:1024
	ds_read_b128 v[170:173], v174 offset:2048
	ds_read_b128 v[174:177], v174 offset:3072
	s_add_u32 s46, s46, 0x80000
	s_addc_u32 s47, s47, 0
	s_mov_b32 m0, s30
	ds_read_b128 v[178:181], v149 offset:32768
	ds_read_b128 v[182:185], v149 offset:33792
	ds_read_b128 v[186:189], v149 offset:34816
	ds_read_b128 v[190:193], v149 offset:35840
	ds_read_b128 v[194:197], v149 offset:36864
	ds_read_b128 v[198:201], v149 offset:37888
	ds_read_b128 v[202:205], v149 offset:38912
	ds_read_b128 v[210:213], v149 offset:39936
	global_load_lds_dwordx4 v136, s[46:47]
	s_mov_b32 m0, s48
	s_nop 0
	global_load_lds_dwordx4 v134, s[46:47]
	s_waitcnt vmcnt(8)
	s_waitcnt lgkmcnt(0)
	s_barrier
	s_waitcnt lgkmcnt(0)
	v_mfma_f32_16x16x32_bf16 v[128:131], v[142:145], v[178:181], v[128:131]
	v_mfma_f32_16x16x32_bf16 v[128:131], v[150:153], v[182:185], v[128:131]
	v_mfma_f32_16x16x32_bf16 v[124:127], v[154:157], v[178:181], v[124:127]
	v_mfma_f32_16x16x32_bf16 v[124:127], v[158:161], v[182:185], v[124:127]
	v_mfma_f32_16x16x32_bf16 v[120:123], v[142:145], v[186:189], v[120:123]
	v_mfma_f32_16x16x32_bf16 v[120:123], v[150:153], v[190:193], v[120:123]
	v_mfma_f32_16x16x32_bf16 v[112:115], v[154:157], v[186:189], v[112:115]
	v_mfma_f32_16x16x32_bf16 v[112:115], v[158:161], v[190:193], v[112:115]
	v_mfma_f32_16x16x32_bf16 v[104:107], v[142:145], v[194:197], v[104:107]
	v_mfma_f32_16x16x32_bf16 v[104:107], v[150:153], v[198:201], v[104:107]
	v_mfma_f32_16x16x32_bf16 v[96:99], v[154:157], v[194:197], v[96:99]
	v_mfma_f32_16x16x32_bf16 v[96:99], v[158:161], v[198:201], v[96:99]
	v_mfma_f32_16x16x32_bf16 v[88:91], v[142:145], v[202:205], v[88:91]
	v_mfma_f32_16x16x32_bf16 v[88:91], v[150:153], v[210:213], v[88:91]
	v_mfma_f32_16x16x32_bf16 v[80:83], v[154:157], v[202:205], v[80:83]
	v_mfma_f32_16x16x32_bf16 v[80:83], v[158:161], v[210:213], v[80:83]
	v_mfma_f32_16x16x32_bf16 v[116:119], v[162:165], v[178:181], v[116:119]
	v_mfma_f32_16x16x32_bf16 v[116:119], v[166:169], v[182:185], v[116:119]
	v_mfma_f32_16x16x32_bf16 v[108:111], v[170:173], v[178:181], v[108:111]
	v_mfma_f32_16x16x32_bf16 v[108:111], v[174:177], v[182:185], v[108:111]
	v_mfma_f32_16x16x32_bf16 v[100:103], v[162:165], v[186:189], v[100:103]
	v_mfma_f32_16x16x32_bf16 v[100:103], v[166:169], v[190:193], v[100:103]
	v_mfma_f32_16x16x32_bf16 v[92:95], v[170:173], v[186:189], v[92:95]
	v_mfma_f32_16x16x32_bf16 v[92:95], v[174:177], v[190:193], v[92:95]
	v_mfma_f32_16x16x32_bf16 v[84:87], v[162:165], v[194:197], v[84:87]
	v_mfma_f32_16x16x32_bf16 v[84:87], v[166:169], v[198:201], v[84:87]
	v_mfma_f32_16x16x32_bf16 v[76:79], v[170:173], v[194:197], v[76:79]
	v_mfma_f32_16x16x32_bf16 v[76:79], v[174:177], v[198:201], v[76:79]
	v_mfma_f32_16x16x32_bf16 v[72:75], v[162:165], v[202:205], v[72:75]
	v_mfma_f32_16x16x32_bf16 v[72:75], v[166:169], v[210:213], v[72:75]
	v_mfma_f32_16x16x32_bf16 v[68:71], v[170:173], v[202:205], v[68:71]
	v_mfma_f32_16x16x32_bf16 v[68:71], v[174:177], v[210:213], v[68:71]
	s_barrier
	s_add_u32 s96, s46, 0xfff80080
	s_addc_u32 s97, s47, -1
	s_add_i32 s46, s57, s21
	s_mov_b32 m0, s46
	ds_read_b128 v[178:181], v149 offset:49152
	ds_read_b128 v[182:185], v149 offset:50176
	ds_read_b128 v[186:189], v149 offset:51200
	ds_read_b128 v[190:193], v149 offset:52224
	ds_read_b128 v[194:197], v149 offset:53248
	ds_read_b128 v[198:201], v149 offset:54272
	ds_read_b128 v[202:205], v149 offset:55296
	ds_read_b128 v[210:213], v149 offset:56320
	s_add_u32 s98, s44, 0x80
	s_addc_u32 s99, s45, 0
	global_load_lds_dwordx4 v2, s[98:99]
	s_add_i32 m0, s46, 0x2000
	s_add_u32 s44, s44, 0x80080
	s_addc_u32 s45, s45, 0
	s_add_i32 s46, s58, s21
	global_load_lds_dwordx4 v132, s[98:99]
	s_mov_b32 m0, s46
	s_nop 0
	global_load_lds_dwordx4 v2, s[44:45]
	s_add_i32 m0, s46, 0x2000
	s_nop 0
	global_load_lds_dwordx4 v132, s[44:45]
	s_mov_b32 m0, s49
	s_nop 0
	global_load_lds_dwordx4 v136, s[96:97]
	s_mov_b32 m0, s50
	s_nop 0
	global_load_lds_dwordx4 v134, s[96:97]
	s_waitcnt vmcnt(8)
	s_waitcnt lgkmcnt(0)
	s_barrier
	s_waitcnt lgkmcnt(0)
	v_mfma_f32_16x16x32_bf16 v[64:67], v[142:145], v[178:181], v[64:67]
	v_mfma_f32_16x16x32_bf16 v[64:67], v[150:153], v[182:185], v[64:67]
	v_mfma_f32_16x16x32_bf16 v[60:63], v[154:157], v[178:181], v[60:63]
	v_mfma_f32_16x16x32_bf16 v[60:63], v[158:161], v[182:185], v[60:63]
	v_mfma_f32_16x16x32_bf16 v[56:59], v[142:145], v[186:189], v[56:59]
	v_mfma_f32_16x16x32_bf16 v[56:59], v[150:153], v[190:193], v[56:59]
	v_mfma_f32_16x16x32_bf16 v[48:51], v[154:157], v[186:189], v[48:51]
	v_mfma_f32_16x16x32_bf16 v[48:51], v[158:161], v[190:193], v[48:51]
	v_mfma_f32_16x16x32_bf16 v[40:43], v[142:145], v[194:197], v[40:43]
	v_mfma_f32_16x16x32_bf16 v[40:43], v[150:153], v[198:201], v[40:43]
	v_mfma_f32_16x16x32_bf16 v[32:35], v[154:157], v[194:197], v[32:35]
	v_mfma_f32_16x16x32_bf16 v[32:35], v[158:161], v[198:201], v[32:35]
	v_mfma_f32_16x16x32_bf16 v[24:27], v[142:145], v[202:205], v[24:27]
	v_mfma_f32_16x16x32_bf16 v[24:27], v[150:153], v[210:213], v[24:27]
	v_mfma_f32_16x16x32_bf16 v[16:19], v[154:157], v[202:205], v[16:19]
	v_mfma_f32_16x16x32_bf16 v[16:19], v[158:161], v[210:213], v[16:19]
	v_mfma_f32_16x16x32_bf16 v[52:55], v[162:165], v[178:181], v[52:55]
	v_mfma_f32_16x16x32_bf16 v[52:55], v[166:169], v[182:185], v[52:55]
	v_mfma_f32_16x16x32_bf16 v[44:47], v[170:173], v[178:181], v[44:47]
	v_mfma_f32_16x16x32_bf16 v[44:47], v[174:177], v[182:185], v[44:47]
	v_mfma_f32_16x16x32_bf16 v[36:39], v[162:165], v[186:189], v[36:39]
	v_mfma_f32_16x16x32_bf16 v[36:39], v[166:169], v[190:193], v[36:39]
	v_mfma_f32_16x16x32_bf16 v[28:31], v[170:173], v[186:189], v[28:31]
	v_mfma_f32_16x16x32_bf16 v[28:31], v[174:177], v[190:193], v[28:31]
	v_mfma_f32_16x16x32_bf16 v[20:23], v[162:165], v[194:197], v[20:23]
	v_mfma_f32_16x16x32_bf16 v[20:23], v[166:169], v[198:201], v[20:23]
	v_mfma_f32_16x16x32_bf16 v[12:15], v[170:173], v[194:197], v[12:15]
	v_mfma_f32_16x16x32_bf16 v[12:15], v[174:177], v[198:201], v[12:15]
	v_mfma_f32_16x16x32_bf16 v[8:11], v[162:165], v[202:205], v[8:11]
	v_mfma_f32_16x16x32_bf16 v[8:11], v[166:169], v[210:213], v[8:11]
	v_mfma_f32_16x16x32_bf16 v[4:7], v[170:173], v[202:205], v[4:7]
	v_mfma_f32_16x16x32_bf16 v[4:7], v[174:177], v[210:213], v[4:7]
	s_barrier
; __device__ __forceinline__ unsigned cvt_pk_bf16(float lo, float hi) { unsigned r; asm volatile("v_cvt_pk_bf16_f32 %0, %1, %2" : "=v"(r) : "v"(lo), "v"(hi)); return r; }
; #define PG8_WAIT_V(n) asm volatile("s_waitcnt vmcnt(" #n ")" ::: "memory")
; #define PG8_BAR __builtin_amdgcn_s_barrier()
;     __device__ __forceinline__ void operator()(const f32x4 (&acc)[2][2][4][2], const Unit& u, int wr, int wc, int fr, int fq) const {
;         const int row0 = u.pm * BM + wr * 64 + fr; const int col0 = u.pn * BM + wc * 32 + 8 * fq;
; #pragma unroll
;         for (int ai = 0; ai < 2; ++ai)
; #pragma unroll
;             for (int m = 0; m < 4; ++m) { bf16_t* rowp = O + (size_t)(row0 + ai * HALF + m * 16) * ldc + col0;
; #pragma unroll
;                 for (int bj = 0; bj < 2; ++bj) { const f32x4 v0 = acc[ai][bj][m][0], v1 = acc[ai][bj][m][1];
;                     u32x4 w; w.x = cvt_pk_bf16(v0[0], v0[1]); w.y = cvt_pk_bf16(v0[2], v0[3]); w.z = cvt_pk_bf16(v1[0], v1[1]); w.w = cvt_pk_bf16(v1[2], v1[3]);
;                     *(u32x4*)(rowp + bj * HALF) = w; } }
; template <class Epi, class Sched, bool ALIGN_EPI = true>
; __device__ __forceinline__ void gemm_phase(PG8_LAS unsigned char* lds, const Gemm g, const Sched& S, const Epi& E, const int tid) {
;     ...
;         }
;         if constexpr (ALIGN_EPI) { if (wr == 0) PG8_BAR; }
;         E(acc, cur, wr, wc, fr, fq); S.done(cur);
;         if (!has_next) break;
; #pragma unroll
;         for (int a = 0; a < 2; ++a)
; #pragma unroll
;             for (int b = 0; b < 2; ++b)
; #pragma unroll
;                 for (int m = 0; m < 4; ++m)
; #pragma unroll
;                     for (int n = 0; n < 2; ++n) acc[a][b][m][n] = (f32x4){0.f, 0.f, 0.f, 0.f};
;         cur = nxt; cA = nA; cB = nB; ++ui;
;         if constexpr (ALIGN_EPI) { if (wr == 1) PG8_BAR; }
;     }
;     PG8_WAIT_V(0);
;     if constexpr (!ALIGN_EPI) { if (wr == 0) PG8_BAR; }
;     PG8_BAR;
	s_add_i32 s56, s56, 2
	s_add_u32 s42, s42, 0x100
	s_addc_u32 s43, s43, 0
	s_add_u32 s54, s54, 0x100
	s_addc_u32 s55, s55, 0
	s_cmp_gt_u32 s56, 29
	s_cbranch_scc0 .LBB0_514
	v_lshl_or_b32 v144, s10, 8, v148
	v_lshl_add_u32 v152, s6, 8, v146
	v_ashrrev_i32_e32 v145, 31, v144
	v_mov_b64_e32 v[142:143], s[0:1]
	s_movk_i32 s3, 0x3200
	v_mad_i64_i32 v[150:151], s[42:43], v152, s3, v[142:143]
	v_lshlrev_b64 v[144:145], 1, v[144:145]
	v_lshl_add_u64 v[150:151], v[150:151], 0, v[144:145]
	v_cvt_pk_bf16_f32 v128, v128, v129
	v_cvt_pk_bf16_f32 v129, v130, v131
	v_cvt_pk_bf16_f32 v130, v124, v125
	v_cvt_pk_bf16_f32 v131, v126, v127
	global_store_dwordx4 v[150:151], v[128:131], off
	v_cvt_pk_bf16_f32 v116, v116, v117
	v_cvt_pk_bf16_f32 v117, v118, v119
	v_cvt_pk_bf16_f32 v118, v108, v109
	v_or_b32_e32 v108, 16, v152
	v_mad_i64_i32 v[108:109], s[42:43], v108, s3, v[142:143]
	v_cvt_pk_bf16_f32 v119, v110, v111
	global_store_dwordx4 v[150:151], v[116:119], off offset:256
	s_and_b64 vcc, exec, s[4:5]
	s_mov_b32 s10, s22
	v_lshl_add_u64 v[116:117], v[108:109], 0, v[144:145]
	v_cvt_pk_bf16_f32 v108, v120, v121
	v_cvt_pk_bf16_f32 v109, v122, v123
	v_cvt_pk_bf16_f32 v110, v112, v113
	v_cvt_pk_bf16_f32 v111, v114, v115
	global_store_dwordx4 v[116:117], v[108:111], off
	v_cvt_pk_bf16_f32 v100, v100, v101
	v_cvt_pk_bf16_f32 v101, v102, v103
	v_cvt_pk_bf16_f32 v102, v92, v93
	v_or_b32_e32 v92, 32, v152
	v_mad_i64_i32 v[92:93], s[42:43], v92, s3, v[142:143]
	v_cvt_pk_bf16_f32 v103, v94, v95
	global_store_dwordx4 v[116:117], v[100:103], off offset:256
	s_mov_b32 s6, s12
	s_mov_b64 s[44:45], s[40:41]
	v_lshl_add_u64 v[100:101], v[92:93], 0, v[144:145]
	v_cvt_pk_bf16_f32 v92, v104, v105
	v_cvt_pk_bf16_f32 v93, v106, v107
	v_cvt_pk_bf16_f32 v94, v96, v97
	v_cvt_pk_bf16_f32 v95, v98, v99
	global_store_dwordx4 v[100:101], v[92:95], off
	v_cvt_pk_bf16_f32 v84, v84, v85
	v_cvt_pk_bf16_f32 v85, v86, v87
	v_cvt_pk_bf16_f32 v86, v76, v77
	v_or_b32_e32 v76, 48, v152
	v_mad_i64_i32 v[76:77], s[42:43], v76, s3, v[142:143]
	v_cvt_pk_bf16_f32 v87, v78, v79
	global_store_dwordx4 v[100:101], v[84:87], off offset:256
	s_nop 1
	v_lshl_add_u64 v[84:85], v[76:77], 0, v[144:145]
	v_cvt_pk_bf16_f32 v76, v88, v89
	v_cvt_pk_bf16_f32 v77, v90, v91
	v_cvt_pk_bf16_f32 v78, v80, v81
	v_cvt_pk_bf16_f32 v79, v82, v83
	global_store_dwordx4 v[84:85], v[76:79], off
	v_cvt_pk_bf16_f32 v72, v72, v73
	v_cvt_pk_bf16_f32 v73, v74, v75
	v_cvt_pk_bf16_f32 v74, v68, v69
	v_add_u32_e32 v68, 0x80, v152
	v_mad_i64_i32 v[68:69], s[42:43], v68, s3, v[142:143]
	v_lshl_add_u64 v[68:69], v[68:69], 0, v[144:145]
	v_cvt_pk_bf16_f32 v75, v70, v71
	global_store_dwordx4 v[84:85], v[72:75], off offset:256
	v_cvt_pk_bf16_f32 v64, v64, v65
	v_cvt_pk_bf16_f32 v65, v66, v67
	v_cvt_pk_bf16_f32 v66, v60, v61
	v_cvt_pk_bf16_f32 v67, v62, v63
	global_store_dwordx4 v[68:69], v[64:67], off
	v_cvt_pk_bf16_f32 v52, v52, v53
	v_cvt_pk_bf16_f32 v53, v54, v55
	v_cvt_pk_bf16_f32 v54, v44, v45
	v_add_u32_e32 v44, 0x90, v152
	v_mad_i64_i32 v[44:45], s[42:43], v44, s3, v[142:143]
	v_cvt_pk_bf16_f32 v55, v46, v47
	global_store_dwordx4 v[68:69], v[52:55], off offset:256
	s_nop 1
	v_lshl_add_u64 v[52:53], v[44:45], 0, v[144:145]
	v_cvt_pk_bf16_f32 v44, v56, v57
	v_cvt_pk_bf16_f32 v45, v58, v59
	v_cvt_pk_bf16_f32 v46, v48, v49
	v_cvt_pk_bf16_f32 v47, v50, v51
	global_store_dwordx4 v[52:53], v[44:47], off
	v_cvt_pk_bf16_f32 v36, v36, v37
	v_cvt_pk_bf16_f32 v37, v38, v39
	v_cvt_pk_bf16_f32 v38, v28, v29
	v_add_u32_e32 v28, 0xa0, v152
	v_mad_i64_i32 v[28:29], s[42:43], v28, s3, v[142:143]
	v_cvt_pk_bf16_f32 v39, v30, v31
	global_store_dwordx4 v[52:53], v[36:39], off offset:256
	s_nop 1
	v_lshl_add_u64 v[36:37], v[28:29], 0, v[144:145]
	v_cvt_pk_bf16_f32 v28, v40, v41
	v_cvt_pk_bf16_f32 v29, v42, v43
	v_cvt_pk_bf16_f32 v30, v32, v33
	v_cvt_pk_bf16_f32 v31, v34, v35
	global_store_dwordx4 v[36:37], v[28:31], off
	v_cvt_pk_bf16_f32 v20, v20, v21
	v_cvt_pk_bf16_f32 v21, v22, v23
	v_cvt_pk_bf16_f32 v22, v12, v13
	v_add_u32_e32 v12, 0xb0, v152
	v_mad_i64_i32 v[12:13], s[42:43], v12, s3, v[142:143]
	v_cvt_pk_bf16_f32 v23, v14, v15
	global_store_dwordx4 v[36:37], v[20:23], off offset:256
	s_mov_b64 s[42:43], s[38:39]
	s_nop 0
	v_lshl_add_u64 v[20:21], v[12:13], 0, v[144:145]
	v_cvt_pk_bf16_f32 v12, v24, v25
	v_cvt_pk_bf16_f32 v13, v26, v27
	v_cvt_pk_bf16_f32 v14, v16, v17
	v_cvt_pk_bf16_f32 v15, v18, v19
	global_store_dwordx4 v[20:21], v[12:15], off
	v_cvt_pk_bf16_f32 v8, v8, v9
	v_cvt_pk_bf16_f32 v9, v10, v11
	v_cvt_pk_bf16_f32 v10, v4, v5
	v_cvt_pk_bf16_f32 v11, v6, v7
	global_store_dwordx4 v[20:21], v[8:11], off offset:256
	s_cbranch_vccz .LBB0_507
	s_waitcnt vmcnt(0)
	s_cmpk_gt_u32 s8, 0xff
	s_cbranch_scc1 .LBB0_518
	s_barrier

; #define PG8_STAGE(bufoff, gbase, voff) do { _Pragma("unroll") for (int _i = 0; _i < 2; ++_i) \
;         __builtin_amdgcn_global_load_lds((const unsigned*)((const char*)(gbase) + (voff)[_i]), (PG8_LAS unsigned*)(lds + (bufoff) + ldsw + _i * 8192), 16, 0, 0); } while (0)
; #define PG8_LDA(dst, b, h) do { _Pragma("unroll") for (int m = 0; m < 4; ++m) _Pragma("unroll") for (int k = 0; k < 2; ++k) dst[m][k] = *(const PG8_LAS bf16x8*)(lds + PG8_SA(b, h) + aoff + m * 2048 + k * 1024); } while (0)
; #define PG8_LDB(dst, b, h) do { _Pragma("unroll") for (int n = 0; n < 2; ++n) _Pragma("unroll") for (int k = 0; k < 2; ++k) dst[n][k] = *(const PG8_LAS bf16x8*)(lds + PG8_SB(b, h) + boff + n * 2048 + k * 1024); } while (0)
; #define PG8_MMA(ai, bj, At, Bt) do { __builtin_amdgcn_s_setprio(1); _Pragma("unroll") for (int m = 0; m < 4; ++m) _Pragma("unroll") for (int n = 0; n < 2; ++n) _Pragma("unroll") for (int k = 0; k < 2; ++k) \
;         acc[ai][bj][m][n] = __builtin_amdgcn_mfma_f32_16x16x32_bf16(Bt[n][k], At[m][k], acc[ai][bj][m][n], 0, 0, 0); __builtin_amdgcn_s_setprio(0); } while (0)
; #define PG8_WAIT_V(n) asm volatile("s_waitcnt vmcnt(" #n ")" ::: "memory")
; #define PG8_WAIT_L(n) asm volatile("s_waitcnt lgkmcnt(" #n ")" ::: "memory")
; #define PG8_BAR __builtin_amdgcn_s_barrier()
; template <class Epi, class Sched, bool ALIGN_EPI = true>
; __device__ __forceinline__ void gemm_phase(PG8_LAS unsigned char* lds, const Gemm g, const Sched& S, const Epi& E, const int tid) {
;     ...
;             const bool last = (t == nt - 2);
;             const char* a1 = cA + (size_t)(t + 1) * kstep;
;             const char* a2 = last ? nA : cA + (size_t)(t + 2) * kstep; const char* b2 = last ? nB : cB + (size_t)(t + 2) * kstep;
;             const char* a3 = a2 + kstep; const char* b3 = b2 + kstep;
;             if (last && has_next) S.a_ready(nxt);
;             PG8_LDB(B0, 0, 0); PG8_LDB(B1, 0, 1); PG8_SCHED; PG8_LDA(At, 0, 0); PG8_STAGE(PG8_SA(1, 1), a1 + hstepA, voffA);
;             PG8_WAIT_V(8); PG8_WAIT_L(0); PG8_BAR; PG8_MMA(0, 0, At, B0); PG8_MMA(0, 1, At, B1); PG8_BAR; PG8_SCHED;
;             PG8_LDA(At, 0, 1); PG8_STAGE(PG8_SB(0, 0), b2, voffB); PG8_STAGE(PG8_SB(0, 1), b2 + hstepB, voffB); PG8_STAGE(PG8_SA(0, 0), a2, voffA);
;             PG8_WAIT_V(8); PG8_WAIT_L(0); PG8_BAR; PG8_MMA(1, 0, At, B0); PG8_MMA(1, 1, At, B1); PG8_BAR; PG8_SCHED;
.LBB0_1087:
	s_add_i32 s45, s22, 2
	s_add_u32 s15, s12, 0xfff80080
	s_addc_u32 s16, s13, -1
	s_add_i32 s17, 0, 0x10000
	s_cmp_eq_u32 s1, s22
	s_cselect_b32 s55, s51, s16
	s_cselect_b32 s54, s50, s15
	s_cselect_b32 s23, s53, s21
	s_cselect_b32 s22, s52, s20
	s_add_i32 s15, 0, 0x14000
	v_add_u32_e32 v72, s17, v251
	v_add_u32_e32 v128, s15, v251
	ds_read_b128 v[56:59], v72
	ds_read_b128 v[64:67], v72 offset:1024
	ds_read_b128 v[68:71], v72 offset:2048
	ds_read_b128 v[72:75], v72 offset:3072
	ds_read_b128 v[92:95], v128
	ds_read_b128 v[104:107], v128 offset:1024
	ds_read_b128 v[116:119], v128 offset:2048
	ds_read_b128 v[128:131], v128 offset:3072
	s_add_i32 m0, s11, 0xc000
	ds_read_b128 v[140:143], v252
	ds_read_b128 v[152:155], v252 offset:1024
	ds_read_b128 v[156:159], v252 offset:2048
	ds_read_b128 v[160:163], v252 offset:3072
	ds_read_b128 v[172:175], v252 offset:4096
	ds_read_b128 v[184:187], v252 offset:5120
	ds_read_b128 v[188:191], v252 offset:6144
	ds_read_b128 v[192:195], v252 offset:7168
	global_load_lds_dwordx4 v216, s[12:13]
	s_add_i32 m0, s11, 0xe000
	s_nop 0
	global_load_lds_dwordx4 v218, s[12:13]
	s_waitcnt vmcnt(8)
	s_waitcnt lgkmcnt(0)
	s_barrier
	s_waitcnt lgkmcnt(0)
	v_mfma_f32_16x16x32_bf16 v[180:183], v[56:59], v[140:143], v[180:183]
	v_mfma_f32_16x16x32_bf16 v[180:183], v[64:67], v[152:155], v[180:183]
	v_mfma_f32_16x16x32_bf16 v[176:179], v[68:71], v[140:143], v[176:179]
	v_mfma_f32_16x16x32_bf16 v[176:179], v[72:75], v[152:155], v[176:179]
	v_mfma_f32_16x16x32_bf16 v[148:151], v[56:59], v[156:159], v[148:151]
	v_mfma_f32_16x16x32_bf16 v[148:151], v[64:67], v[160:163], v[148:151]
	v_mfma_f32_16x16x32_bf16 v[144:147], v[68:71], v[156:159], v[144:147]
	v_mfma_f32_16x16x32_bf16 v[144:147], v[72:75], v[160:163], v[144:147]
	v_mfma_f32_16x16x32_bf16 v[124:127], v[56:59], v[172:175], v[124:127]
	v_mfma_f32_16x16x32_bf16 v[124:127], v[64:67], v[184:187], v[124:127]
	v_mfma_f32_16x16x32_bf16 v[120:123], v[68:71], v[172:175], v[120:123]
	v_mfma_f32_16x16x32_bf16 v[120:123], v[72:75], v[184:187], v[120:123]
	v_mfma_f32_16x16x32_bf16 v[100:103], v[56:59], v[188:191], v[100:103]
	v_mfma_f32_16x16x32_bf16 v[100:103], v[64:67], v[192:195], v[100:103]
	v_mfma_f32_16x16x32_bf16 v[96:99], v[68:71], v[188:191], v[96:99]
	v_mfma_f32_16x16x32_bf16 v[96:99], v[72:75], v[192:195], v[96:99]
	v_mfma_f32_16x16x32_bf16 v[168:171], v[92:95], v[140:143], v[168:171]
	v_mfma_f32_16x16x32_bf16 v[136:139], v[92:95], v[156:159], v[136:139]
	v_mfma_f32_16x16x32_bf16 v[132:135], v[116:119], v[156:159], v[132:135]
	v_mfma_f32_16x16x32_bf16 v[112:115], v[92:95], v[172:175], v[112:115]
	v_mfma_f32_16x16x32_bf16 v[108:111], v[116:119], v[172:175], v[108:111]
	v_mfma_f32_16x16x32_bf16 v[88:91], v[92:95], v[188:191], v[88:91]
	v_mfma_f32_16x16x32_bf16 v[84:87], v[116:119], v[188:191], v[84:87]
	v_mfma_f32_16x16x32_bf16 v[168:171], v[104:107], v[152:155], v[168:171]
	v_mfma_f32_16x16x32_bf16 v[140:143], v[116:119], v[140:143], v[164:167]
	v_mfma_f32_16x16x32_bf16 v[136:139], v[104:107], v[160:163], v[136:139]
	v_mfma_f32_16x16x32_bf16 v[132:135], v[128:131], v[160:163], v[132:135]
	v_mfma_f32_16x16x32_bf16 v[112:115], v[104:107], v[184:187], v[112:115]
	v_mfma_f32_16x16x32_bf16 v[108:111], v[128:131], v[184:187], v[108:111]
	v_mfma_f32_16x16x32_bf16 v[88:91], v[104:107], v[192:195], v[88:91]
	v_mfma_f32_16x16x32_bf16 v[84:87], v[128:131], v[192:195], v[84:87]
	v_mfma_f32_16x16x32_bf16 v[140:143], v[128:131], v[152:155], v[140:143]
	s_barrier
	s_add_i32 s16, s17, s60
	s_mov_b32 m0, s16
	ds_read_b128 v[152:155], v252 offset:16384
	ds_read_b128 v[156:159], v252 offset:17408
	ds_read_b128 v[160:163], v252 offset:18432
	ds_read_b128 v[164:167], v252 offset:19456
	ds_read_b128 v[172:175], v252 offset:20480
	ds_read_b128 v[184:187], v252 offset:21504
	ds_read_b128 v[188:191], v252 offset:22528
	ds_read_b128 v[192:195], v252 offset:23552
	global_load_lds_dwordx4 v2, s[22:23]
	s_add_i32 m0, s16, 0x2000
	s_add_u32 s72, s22, 0x80000
	s_addc_u32 s73, s23, 0
	s_add_i32 s15, s15, s60
	global_load_lds_dwordx4 v214, s[22:23]
	s_mov_b32 m0, s15
	s_nop 0
	global_load_lds_dwordx4 v2, s[72:73]
	s_add_i32 m0, s15, 0x2000
	s_nop 0
	global_load_lds_dwordx4 v214, s[72:73]
	s_mov_b32 m0, s11
	s_nop 0
	global_load_lds_dwordx4 v210, s[54:55]
	s_mov_b32 m0, s61
	s_nop 0
	global_load_lds_dwordx4 v212, s[54:55]
	s_waitcnt vmcnt(8)
	s_waitcnt lgkmcnt(0)
	s_barrier
	s_waitcnt lgkmcnt(0)
	v_mfma_f32_16x16x32_bf16 v[80:83], v[56:59], v[152:155], v[80:83]
	v_mfma_f32_16x16x32_bf16 v[80:83], v[64:67], v[156:159], v[80:83]
	v_mfma_f32_16x16x32_bf16 v[76:79], v[68:71], v[152:155], v[76:79]
	v_mfma_f32_16x16x32_bf16 v[76:79], v[72:75], v[156:159], v[76:79]
	v_mfma_f32_16x16x32_bf16 v[48:51], v[56:59], v[160:163], v[48:51]
	v_mfma_f32_16x16x32_bf16 v[48:51], v[64:67], v[164:167], v[48:51]
	v_mfma_f32_16x16x32_bf16 v[44:47], v[68:71], v[160:163], v[44:47]
	v_mfma_f32_16x16x32_bf16 v[44:47], v[72:75], v[164:167], v[44:47]
	v_mfma_f32_16x16x32_bf16 v[32:35], v[56:59], v[172:175], v[32:35]
	v_mfma_f32_16x16x32_bf16 v[32:35], v[64:67], v[184:187], v[32:35]
	v_mfma_f32_16x16x32_bf16 v[28:31], v[68:71], v[172:175], v[28:31]
	v_mfma_f32_16x16x32_bf16 v[28:31], v[72:75], v[184:187], v[28:31]
	v_mfma_f32_16x16x32_bf16 v[16:19], v[56:59], v[188:191], v[16:19]
	v_mfma_f32_16x16x32_bf16 v[16:19], v[64:67], v[192:195], v[16:19]
	v_mfma_f32_16x16x32_bf16 v[12:15], v[68:71], v[188:191], v[12:15]
	v_mfma_f32_16x16x32_bf16 v[12:15], v[72:75], v[192:195], v[12:15]
	v_mfma_f32_16x16x32_bf16 v[52:55], v[116:119], v[152:155], v[52:55]
	v_mfma_f32_16x16x32_bf16 v[40:43], v[92:95], v[160:163], v[40:43]
	v_mfma_f32_16x16x32_bf16 v[36:39], v[116:119], v[160:163], v[36:39]
	v_mfma_f32_16x16x32_bf16 v[24:27], v[92:95], v[172:175], v[24:27]
	v_mfma_f32_16x16x32_bf16 v[20:23], v[116:119], v[172:175], v[20:23]
	v_mfma_f32_16x16x32_bf16 v[8:11], v[92:95], v[188:191], v[8:11]
	v_mfma_f32_16x16x32_bf16 v[4:7], v[116:119], v[188:191], v[4:7]
	v_mfma_f32_16x16x32_bf16 v[56:59], v[92:95], v[152:155], v[60:63]
	v_mfma_f32_16x16x32_bf16 v[52:55], v[128:131], v[156:159], v[52:55]
	v_mfma_f32_16x16x32_bf16 v[40:43], v[104:107], v[164:167], v[40:43]
	v_mfma_f32_16x16x32_bf16 v[36:39], v[128:131], v[164:167], v[36:39]
	v_mfma_f32_16x16x32_bf16 v[24:27], v[104:107], v[184:187], v[24:27]
	v_mfma_f32_16x16x32_bf16 v[20:23], v[128:131], v[184:187], v[20:23]
	v_mfma_f32_16x16x32_bf16 v[8:11], v[104:107], v[192:195], v[8:11]
	v_mfma_f32_16x16x32_bf16 v[4:7], v[128:131], v[192:195], v[4:7]
	v_mfma_f32_16x16x32_bf16 v[56:59], v[104:107], v[156:159], v[56:59]
	s_barrier
; #define PG8_STAGE(bufoff, gbase, voff) do { _Pragma("unroll") for (int _i = 0; _i < 2; ++_i) \
;         __builtin_amdgcn_global_load_lds((const unsigned*)((const char*)(gbase) + (voff)[_i]), (PG8_LAS unsigned*)(lds + (bufoff) + ldsw + _i * 8192), 16, 0, 0); } while (0)
; #define PG8_LDA(dst, b, h) do { _Pragma("unroll") for (int m = 0; m < 4; ++m) _Pragma("unroll") for (int k = 0; k < 2; ++k) dst[m][k] = *(const PG8_LAS bf16x8*)(lds + PG8_SA(b, h) + aoff + m * 2048 + k * 1024); } while (0)
; #define PG8_LDB(dst, b, h) do { _Pragma("unroll") for (int n = 0; n < 2; ++n) _Pragma("unroll") for (int k = 0; k < 2; ++k) dst[n][k] = *(const PG8_LAS bf16x8*)(lds + PG8_SB(b, h) + boff + n * 2048 + k * 1024); } while (0)
; #define PG8_MMA(ai, bj, At, Bt) do { __builtin_amdgcn_s_setprio(1); _Pragma("unroll") for (int m = 0; m < 4; ++m) _Pragma("unroll") for (int n = 0; n < 2; ++n) _Pragma("unroll") for (int k = 0; k < 2; ++k) \
;         acc[ai][bj][m][n] = __builtin_amdgcn_mfma_f32_16x16x32_bf16(Bt[n][k], At[m][k], acc[ai][bj][m][n], 0, 0, 0); __builtin_amdgcn_s_setprio(0); } while (0)
; #define PG8_WAIT_V(n) asm volatile("s_waitcnt vmcnt(" #n ")" ::: "memory")
; #define PG8_WAIT_L(n) asm volatile("s_waitcnt lgkmcnt(" #n ")" ::: "memory")
; #define PG8_BAR __builtin_amdgcn_s_barrier()
; #define PG8_SCHED __builtin_amdgcn_sched_barrier(0)
; template <class Epi, class Sched, bool ALIGN_EPI = true>
; __device__ __forceinline__ void gemm_phase(PG8_LAS unsigned char* lds, const Gemm g, const Sched& S, const Epi& E, const int tid) {
;     ...
;             PG8_LDB(B0, 1, 0); PG8_LDB(B1, 1, 1); PG8_SCHED; PG8_LDA(At, 1, 0); PG8_STAGE(PG8_SA(0, 1), a2 + hstepA, voffA);
;             PG8_WAIT_V(8); PG8_WAIT_L(0); PG8_BAR; PG8_MMA(0, 0, At, B0); PG8_MMA(0, 1, At, B1); PG8_BAR; PG8_SCHED;
;             PG8_LDA(At, 1, 1); PG8_STAGE(PG8_SB(1, 0), b3, voffB); PG8_STAGE(PG8_SB(1, 1), b3 + hstepB, voffB); PG8_STAGE(PG8_SA(1, 0), a3, voffA);
;             PG8_WAIT_V(8); PG8_WAIT_L(0); PG8_BAR; PG8_MMA(1, 0, At, B0); PG8_MMA(1, 1, At, B1); PG8_BAR; PG8_SCHED;
;         }
;         if constexpr (ALIGN_EPI) { if (wr == 0) PG8_BAR; }
;         E(acc, cur, wr, wc, fr, fq); S.done(cur);
;         if (!has_next) break;
	s_add_i32 s15, 0, 0x18000
	s_add_i32 s16, 0, 0x1c000
	v_add_u32_e32 v72, s15, v251
	v_add_u32_e32 v128, s16, v251
	ds_read_b128 v[60:63], v72
	ds_read_b128 v[64:67], v72 offset:1024
	ds_read_b128 v[68:71], v72 offset:2048
	ds_read_b128 v[72:75], v72 offset:3072
	ds_read_b128 v[92:95], v128
	ds_read_b128 v[104:107], v128 offset:1024
	ds_read_b128 v[116:119], v128 offset:2048
	ds_read_b128 v[128:131], v128 offset:3072
	s_add_u32 s54, s54, 0x80000
	s_addc_u32 s55, s55, 0
	s_mov_b32 m0, s62
	ds_read_b128 v[152:155], v252 offset:32768
	ds_read_b128 v[156:159], v252 offset:33792
	ds_read_b128 v[160:163], v252 offset:34816
	ds_read_b128 v[172:175], v252 offset:35840
	ds_read_b128 v[184:187], v252 offset:36864
	ds_read_b128 v[188:191], v252 offset:37888
	ds_read_b128 v[192:195], v252 offset:38912
	ds_read_b128 v[196:199], v252 offset:39936
	global_load_lds_dwordx4 v210, s[54:55]
	s_mov_b32 m0, s63
	s_nop 0
	global_load_lds_dwordx4 v212, s[54:55]
	s_waitcnt vmcnt(8)
	s_waitcnt lgkmcnt(0)
	s_barrier
	s_waitcnt lgkmcnt(0)
	v_mfma_f32_16x16x32_bf16 v[164:167], v[60:63], v[152:155], v[180:183]
	v_mfma_f32_16x16x32_bf16 v[180:183], v[64:67], v[156:159], v[164:167]
	v_mfma_f32_16x16x32_bf16 v[164:167], v[68:71], v[152:155], v[176:179]
	v_mfma_f32_16x16x32_bf16 v[148:151], v[60:63], v[160:163], v[148:151]
	v_mfma_f32_16x16x32_bf16 v[144:147], v[68:71], v[160:163], v[144:147]
	v_mfma_f32_16x16x32_bf16 v[124:127], v[60:63], v[184:187], v[124:127]
	v_mfma_f32_16x16x32_bf16 v[120:123], v[68:71], v[184:187], v[120:123]
	v_mfma_f32_16x16x32_bf16 v[100:103], v[60:63], v[192:195], v[100:103]
	v_mfma_f32_16x16x32_bf16 v[96:99], v[68:71], v[192:195], v[96:99]
	v_mfma_f32_16x16x32_bf16 v[176:179], v[72:75], v[156:159], v[164:167]
	v_mfma_f32_16x16x32_bf16 v[148:151], v[64:67], v[172:175], v[148:151]
	v_mfma_f32_16x16x32_bf16 v[144:147], v[72:75], v[172:175], v[144:147]
	v_mfma_f32_16x16x32_bf16 v[124:127], v[64:67], v[188:191], v[124:127]
	v_mfma_f32_16x16x32_bf16 v[120:123], v[72:75], v[188:191], v[120:123]
	v_mfma_f32_16x16x32_bf16 v[100:103], v[64:67], v[196:199], v[100:103]
	v_mfma_f32_16x16x32_bf16 v[96:99], v[72:75], v[196:199], v[96:99]
	v_mfma_f32_16x16x32_bf16 v[164:167], v[92:95], v[152:155], v[168:171]
	v_mfma_f32_16x16x32_bf16 v[140:143], v[116:119], v[152:155], v[140:143]
	v_mfma_f32_16x16x32_bf16 v[136:139], v[92:95], v[160:163], v[136:139]
	v_mfma_f32_16x16x32_bf16 v[132:135], v[116:119], v[160:163], v[132:135]
	v_mfma_f32_16x16x32_bf16 v[112:115], v[92:95], v[184:187], v[112:115]
	v_mfma_f32_16x16x32_bf16 v[108:111], v[116:119], v[184:187], v[108:111]
	v_mfma_f32_16x16x32_bf16 v[88:91], v[92:95], v[192:195], v[88:91]
	v_mfma_f32_16x16x32_bf16 v[84:87], v[116:119], v[192:195], v[84:87]
	v_mfma_f32_16x16x32_bf16 v[168:171], v[104:107], v[156:159], v[164:167]
	v_mfma_f32_16x16x32_bf16 v[164:167], v[128:131], v[156:159], v[140:143]
	v_mfma_f32_16x16x32_bf16 v[136:139], v[104:107], v[172:175], v[136:139]
	v_mfma_f32_16x16x32_bf16 v[132:135], v[128:131], v[172:175], v[132:135]
	v_mfma_f32_16x16x32_bf16 v[112:115], v[104:107], v[188:191], v[112:115]
	v_mfma_f32_16x16x32_bf16 v[108:111], v[128:131], v[188:191], v[108:111]
	v_mfma_f32_16x16x32_bf16 v[88:91], v[104:107], v[196:199], v[88:91]
	v_mfma_f32_16x16x32_bf16 v[84:87], v[128:131], v[196:199], v[84:87]
	s_barrier
	s_add_i32 s15, s15, s60
	s_mov_b32 m0, s15
	ds_read_b128 v[140:143], v252 offset:49152
	ds_read_b128 v[152:155], v252 offset:50176
	ds_read_b128 v[156:159], v252 offset:51200
	ds_read_b128 v[160:163], v252 offset:52224
	ds_read_b128 v[172:175], v252 offset:53248
	ds_read_b128 v[184:187], v252 offset:54272
	ds_read_b128 v[188:191], v252 offset:55296
	ds_read_b128 v[192:195], v252 offset:56320
	s_add_u32 s98, s22, 0x80
	s_addc_u32 s99, s23, 0
	global_load_lds_dwordx4 v2, s[98:99]
	s_add_i32 m0, s15, 0x2000
	s_add_u32 s22, s22, 0x80080
	s_addc_u32 s23, s23, 0
	s_add_i32 s15, s16, s60
	global_load_lds_dwordx4 v214, s[98:99]
	s_mov_b32 m0, s15
	s_nop 0
	global_load_lds_dwordx4 v2, s[22:23]
	s_add_i32 m0, s15, 0x2000
	s_nop 0
	global_load_lds_dwordx4 v214, s[22:23]
	s_mov_b32 m0, s68
	s_nop 0
	s_add_u32 s98, s54, 0xfff80080
	s_addc_u32 s99, s55, -1
	global_load_lds_dwordx4 v210, s[98:99]
	s_mov_b32 m0, s69
	s_nop 0
	global_load_lds_dwordx4 v212, s[98:99]
	s_waitcnt vmcnt(8)
	s_waitcnt lgkmcnt(0)
	s_barrier
	s_waitcnt lgkmcnt(0)
	v_mfma_f32_16x16x32_bf16 v[80:83], v[60:63], v[140:143], v[80:83]
	v_mfma_f32_16x16x32_bf16 v[80:83], v[64:67], v[152:155], v[80:83]
	v_mfma_f32_16x16x32_bf16 v[76:79], v[68:71], v[140:143], v[76:79]
	v_mfma_f32_16x16x32_bf16 v[76:79], v[72:75], v[152:155], v[76:79]
	v_mfma_f32_16x16x32_bf16 v[48:51], v[60:63], v[156:159], v[48:51]
	v_mfma_f32_16x16x32_bf16 v[48:51], v[64:67], v[160:163], v[48:51]
	v_mfma_f32_16x16x32_bf16 v[44:47], v[68:71], v[156:159], v[44:47]
	v_mfma_f32_16x16x32_bf16 v[44:47], v[72:75], v[160:163], v[44:47]
	v_mfma_f32_16x16x32_bf16 v[32:35], v[60:63], v[172:175], v[32:35]
	v_mfma_f32_16x16x32_bf16 v[32:35], v[64:67], v[184:187], v[32:35]
	v_mfma_f32_16x16x32_bf16 v[28:31], v[68:71], v[172:175], v[28:31]
	v_mfma_f32_16x16x32_bf16 v[28:31], v[72:75], v[184:187], v[28:31]
	v_mfma_f32_16x16x32_bf16 v[16:19], v[60:63], v[188:191], v[16:19]
	v_mfma_f32_16x16x32_bf16 v[16:19], v[64:67], v[192:195], v[16:19]
	v_mfma_f32_16x16x32_bf16 v[12:15], v[68:71], v[188:191], v[12:15]
	v_mfma_f32_16x16x32_bf16 v[12:15], v[72:75], v[192:195], v[12:15]
	v_mfma_f32_16x16x32_bf16 v[56:59], v[92:95], v[140:143], v[56:59]
	v_mfma_f32_16x16x32_bf16 v[52:55], v[116:119], v[140:143], v[52:55]
	v_mfma_f32_16x16x32_bf16 v[40:43], v[92:95], v[156:159], v[40:43]
	v_mfma_f32_16x16x32_bf16 v[36:39], v[116:119], v[156:159], v[36:39]
	v_mfma_f32_16x16x32_bf16 v[24:27], v[92:95], v[172:175], v[24:27]
	v_mfma_f32_16x16x32_bf16 v[20:23], v[116:119], v[172:175], v[20:23]
	v_mfma_f32_16x16x32_bf16 v[8:11], v[92:95], v[188:191], v[8:11]
	v_mfma_f32_16x16x32_bf16 v[4:7], v[116:119], v[188:191], v[4:7]
	v_mfma_f32_16x16x32_bf16 v[60:63], v[104:107], v[152:155], v[56:59]
	v_mfma_f32_16x16x32_bf16 v[52:55], v[128:131], v[152:155], v[52:55]
	v_mfma_f32_16x16x32_bf16 v[40:43], v[104:107], v[160:163], v[40:43]
	v_mfma_f32_16x16x32_bf16 v[36:39], v[128:131], v[160:163], v[36:39]
	v_mfma_f32_16x16x32_bf16 v[24:27], v[104:107], v[184:187], v[24:27]
	v_mfma_f32_16x16x32_bf16 v[20:23], v[128:131], v[184:187], v[20:23]
	v_mfma_f32_16x16x32_bf16 v[8:11], v[104:107], v[192:195], v[8:11]
	v_mfma_f32_16x16x32_bf16 v[4:7], v[128:131], v[192:195], v[4:7]
	s_barrier
	s_add_u32 s12, s12, 0x100
	s_addc_u32 s13, s13, 0
	s_add_u32 s20, s20, 0x100
	s_addc_u32 s21, s21, 0
	s_cmp_ge_i32 s45, s9
	s_mov_b32 s22, s45
	s_cbranch_scc0 .LBB0_1087
	s_and_b64 vcc, exec, s[42:43]
	s_cbranch_vccz .LBB0_1090
	s_barrier

; #define PG8_STAGE(bufoff, gbase, voff) do { _Pragma("unroll") for (int _i = 0; _i < 2; ++_i) \
;         __builtin_amdgcn_global_load_lds((const unsigned*)((const char*)(gbase) + (voff)[_i]), (PG8_LAS unsigned*)(lds + (bufoff) + ldsw + _i * 8192), 16, 0, 0); } while (0)
; #define PG8_LDA(dst, b, h) do { _Pragma("unroll") for (int m = 0; m < 4; ++m) _Pragma("unroll") for (int k = 0; k < 2; ++k) dst[m][k] = *(const PG8_LAS bf16x8*)(lds + PG8_SA(b, h) + aoff + m * 2048 + k * 1024); } while (0)
; #define PG8_LDB(dst, b, h) do { _Pragma("unroll") for (int n = 0; n < 2; ++n) _Pragma("unroll") for (int k = 0; k < 2; ++k) dst[n][k] = *(const PG8_LAS bf16x8*)(lds + PG8_SB(b, h) + boff + n * 2048 + k * 1024); } while (0)
; #define PG8_MMA(ai, bj, At, Bt) do { __builtin_amdgcn_s_setprio(1); _Pragma("unroll") for (int m = 0; m < 4; ++m) _Pragma("unroll") for (int n = 0; n < 2; ++n) _Pragma("unroll") for (int k = 0; k < 2; ++k) \
;         acc[ai][bj][m][n] = __builtin_amdgcn_mfma_f32_16x16x32_bf16(Bt[n][k], At[m][k], acc[ai][bj][m][n], 0, 0, 0); __builtin_amdgcn_s_setprio(0); } while (0)
; #define PG8_WAIT_V(n) asm volatile("s_waitcnt vmcnt(" #n ")" ::: "memory")
; #define PG8_WAIT_L(n) asm volatile("s_waitcnt lgkmcnt(" #n ")" ::: "memory")
; #define PG8_BAR __builtin_amdgcn_s_barrier()
; template <class Epi, class Sched, bool ALIGN_EPI = true>
; __device__ __forceinline__ void gemm_phase(PG8_LAS unsigned char* lds, const Gemm g, const Sched& S, const Epi& E, const int tid) {
;     ...
;             const bool last = (t == nt - 2);
;             const char* a1 = cA + (size_t)(t + 1) * kstep;
;             const char* a2 = last ? nA : cA + (size_t)(t + 2) * kstep; const char* b2 = last ? nB : cB + (size_t)(t + 2) * kstep;
;             const char* a3 = a2 + kstep; const char* b3 = b2 + kstep;
;             if (last && has_next) S.a_ready(nxt);
;             PG8_LDB(B0, 0, 0); PG8_LDB(B1, 0, 1); PG8_SCHED; PG8_LDA(At, 0, 0); PG8_STAGE(PG8_SA(1, 1), a1 + hstepA, voffA);
;             PG8_WAIT_V(8); PG8_WAIT_L(0); PG8_BAR; PG8_MMA(0, 0, At, B0); PG8_MMA(0, 1, At, B1); PG8_BAR; PG8_SCHED;
;             PG8_LDA(At, 0, 1); PG8_STAGE(PG8_SB(0, 0), b2, voffB); PG8_STAGE(PG8_SB(0, 1), b2 + hstepB, voffB); PG8_STAGE(PG8_SA(0, 0), a2, voffA);
;             PG8_WAIT_V(8); PG8_WAIT_L(0); PG8_BAR; PG8_MMA(1, 0, At, B0); PG8_MMA(1, 1, At, B1); PG8_BAR; PG8_SCHED;
.LBB0_1238:
	s_add_u32 s15, s74, 0xfff80080
	s_addc_u32 s16, s75, -1
	s_add_i32 s17, 0, 0x10000
	s_cmp_eq_u32 s21, 28
	s_cselect_b32 s79, s8, s16
	s_cselect_b32 s78, s11, s15
	s_cselect_b32 s77, s13, s20
	s_cselect_b32 s76, s18, s19
	s_add_i32 s15, 0, 0x14000
	v_add_u32_e32 v88, s17, v193
	v_add_u32_e32 v104, s15, v193
	ds_read_b128 v[72:75], v88
	ds_read_b128 v[76:79], v88 offset:1024
	ds_read_b128 v[84:87], v88 offset:2048
	ds_read_b128 v[88:91], v88 offset:3072
	ds_read_b128 v[92:95], v104
	ds_read_b128 v[96:99], v104 offset:1024
	ds_read_b128 v[100:103], v104 offset:2048
	ds_read_b128 v[104:107], v104 offset:3072
	s_add_i32 m0, s86, 0xc000
	ds_read_b128 v[164:167], v200
	ds_read_b128 v[168:171], v200 offset:1024
	ds_read_b128 v[172:175], v200 offset:2048
	ds_read_b128 v[176:179], v200 offset:3072
	ds_read_b128 v[202:205], v200 offset:4096
	ds_read_b128 v[210:213], v200 offset:5120
	ds_read_b128 v[214:217], v200 offset:6144
	ds_read_b128 v[218:221], v200 offset:7168
	global_load_lds_dwordx4 v186, s[74:75]
	s_add_i32 m0, s86, 0xe000
	s_nop 0
	global_load_lds_dwordx4 v188, s[74:75]
	s_waitcnt vmcnt(8)
	s_waitcnt lgkmcnt(0)
	s_barrier
	s_waitcnt lgkmcnt(0)
	v_mfma_f32_16x16x32_bf16 v[160:163], v[72:75], v[164:167], v[160:163]
	v_mfma_f32_16x16x32_bf16 v[160:163], v[76:79], v[168:171], v[160:163]
	v_mfma_f32_16x16x32_bf16 v[156:159], v[84:87], v[164:167], v[156:159]
	v_mfma_f32_16x16x32_bf16 v[156:159], v[88:91], v[168:171], v[156:159]
	v_mfma_f32_16x16x32_bf16 v[144:147], v[72:75], v[172:175], v[144:147]
	v_mfma_f32_16x16x32_bf16 v[144:147], v[76:79], v[176:179], v[144:147]
	v_mfma_f32_16x16x32_bf16 v[140:143], v[84:87], v[172:175], v[140:143]
	v_mfma_f32_16x16x32_bf16 v[140:143], v[88:91], v[176:179], v[140:143]
	v_mfma_f32_16x16x32_bf16 v[128:131], v[72:75], v[202:205], v[128:131]
	v_mfma_f32_16x16x32_bf16 v[128:131], v[76:79], v[210:213], v[128:131]
	v_mfma_f32_16x16x32_bf16 v[124:127], v[84:87], v[202:205], v[124:127]
	v_mfma_f32_16x16x32_bf16 v[124:127], v[88:91], v[210:213], v[124:127]
	v_mfma_f32_16x16x32_bf16 v[80:83], v[72:75], v[214:217], v[80:83]
	v_mfma_f32_16x16x32_bf16 v[80:83], v[76:79], v[218:221], v[80:83]
	v_mfma_f32_16x16x32_bf16 v[68:71], v[84:87], v[214:217], v[68:71]
	v_mfma_f32_16x16x32_bf16 v[68:71], v[88:91], v[218:221], v[68:71]
	v_mfma_f32_16x16x32_bf16 v[152:155], v[92:95], v[164:167], v[152:155]
	v_mfma_f32_16x16x32_bf16 v[152:155], v[96:99], v[168:171], v[152:155]
	v_mfma_f32_16x16x32_bf16 v[148:151], v[100:103], v[164:167], v[148:151]
	v_mfma_f32_16x16x32_bf16 v[148:151], v[104:107], v[168:171], v[148:151]
	v_mfma_f32_16x16x32_bf16 v[136:139], v[92:95], v[172:175], v[136:139]
	v_mfma_f32_16x16x32_bf16 v[136:139], v[96:99], v[176:179], v[136:139]
	v_mfma_f32_16x16x32_bf16 v[132:135], v[100:103], v[172:175], v[132:135]
	v_mfma_f32_16x16x32_bf16 v[132:135], v[104:107], v[176:179], v[132:135]
	v_mfma_f32_16x16x32_bf16 v[120:123], v[92:95], v[202:205], v[120:123]
	v_mfma_f32_16x16x32_bf16 v[120:123], v[96:99], v[210:213], v[120:123]
	v_mfma_f32_16x16x32_bf16 v[116:119], v[100:103], v[202:205], v[116:119]
	v_mfma_f32_16x16x32_bf16 v[116:119], v[104:107], v[210:213], v[116:119]
	v_mfma_f32_16x16x32_bf16 v[112:115], v[92:95], v[214:217], v[112:115]
	v_mfma_f32_16x16x32_bf16 v[112:115], v[96:99], v[218:221], v[112:115]
	v_mfma_f32_16x16x32_bf16 v[108:111], v[100:103], v[214:217], v[108:111]
	v_mfma_f32_16x16x32_bf16 v[108:111], v[104:107], v[218:221], v[108:111]
	s_barrier
	s_add_i32 s16, s17, s85
	s_mov_b32 m0, s16
	ds_read_b128 v[164:167], v200 offset:16384
	ds_read_b128 v[168:171], v200 offset:17408
	ds_read_b128 v[172:175], v200 offset:18432
	ds_read_b128 v[176:179], v200 offset:19456
	ds_read_b128 v[202:205], v200 offset:20480
	ds_read_b128 v[210:213], v200 offset:21504
	ds_read_b128 v[214:217], v200 offset:22528
	ds_read_b128 v[218:221], v200 offset:23552
	global_load_lds_dwordx4 v2, s[76:77]
	s_add_i32 m0, s16, 0x2000
	s_add_u32 s96, s76, 0x80000
	s_addc_u32 s97, s77, 0
	s_add_i32 s15, s15, s85
	global_load_lds_dwordx4 v184, s[76:77]
	s_mov_b32 m0, s15
	s_nop 0
	global_load_lds_dwordx4 v2, s[96:97]
	s_add_i32 m0, s15, 0x2000
	s_nop 0
	global_load_lds_dwordx4 v184, s[96:97]
	s_mov_b32 m0, s86
	s_nop 0
	global_load_lds_dwordx4 v180, s[78:79]
	s_mov_b32 m0, s87
	s_nop 0
	global_load_lds_dwordx4 v182, s[78:79]
	s_waitcnt vmcnt(8)
	s_waitcnt lgkmcnt(0)
	s_barrier
	s_waitcnt lgkmcnt(0)
	v_mfma_f32_16x16x32_bf16 v[64:67], v[72:75], v[164:167], v[64:67]
	v_mfma_f32_16x16x32_bf16 v[64:67], v[76:79], v[168:171], v[64:67]
	v_mfma_f32_16x16x32_bf16 v[60:63], v[84:87], v[164:167], v[60:63]
	v_mfma_f32_16x16x32_bf16 v[60:63], v[88:91], v[168:171], v[60:63]
	v_mfma_f32_16x16x32_bf16 v[48:51], v[72:75], v[172:175], v[48:51]
	v_mfma_f32_16x16x32_bf16 v[48:51], v[76:79], v[176:179], v[48:51]
	v_mfma_f32_16x16x32_bf16 v[44:47], v[84:87], v[172:175], v[44:47]
	v_mfma_f32_16x16x32_bf16 v[44:47], v[88:91], v[176:179], v[44:47]
	v_mfma_f32_16x16x32_bf16 v[32:35], v[72:75], v[202:205], v[32:35]
	v_mfma_f32_16x16x32_bf16 v[32:35], v[76:79], v[210:213], v[32:35]
	v_mfma_f32_16x16x32_bf16 v[28:31], v[84:87], v[202:205], v[28:31]
	v_mfma_f32_16x16x32_bf16 v[28:31], v[88:91], v[210:213], v[28:31]
	v_mfma_f32_16x16x32_bf16 v[8:11], v[72:75], v[214:217], v[8:11]
	v_mfma_f32_16x16x32_bf16 v[8:11], v[76:79], v[218:221], v[8:11]
	v_mfma_f32_16x16x32_bf16 v[4:7], v[84:87], v[214:217], v[4:7]
	v_mfma_f32_16x16x32_bf16 v[4:7], v[88:91], v[218:221], v[4:7]
	v_mfma_f32_16x16x32_bf16 v[56:59], v[92:95], v[164:167], v[56:59]
	v_mfma_f32_16x16x32_bf16 v[56:59], v[96:99], v[168:171], v[56:59]
	v_mfma_f32_16x16x32_bf16 v[52:55], v[100:103], v[164:167], v[52:55]
	v_mfma_f32_16x16x32_bf16 v[52:55], v[104:107], v[168:171], v[52:55]
	v_mfma_f32_16x16x32_bf16 v[40:43], v[92:95], v[172:175], v[40:43]
	v_mfma_f32_16x16x32_bf16 v[40:43], v[96:99], v[176:179], v[40:43]
	v_mfma_f32_16x16x32_bf16 v[36:39], v[100:103], v[172:175], v[36:39]
	v_mfma_f32_16x16x32_bf16 v[36:39], v[104:107], v[176:179], v[36:39]
	v_mfma_f32_16x16x32_bf16 v[24:27], v[92:95], v[202:205], v[24:27]
	v_mfma_f32_16x16x32_bf16 v[24:27], v[96:99], v[210:213], v[24:27]
	v_mfma_f32_16x16x32_bf16 v[20:23], v[100:103], v[202:205], v[20:23]
	v_mfma_f32_16x16x32_bf16 v[20:23], v[104:107], v[210:213], v[20:23]
	v_mfma_f32_16x16x32_bf16 v[16:19], v[92:95], v[214:217], v[16:19]
	v_mfma_f32_16x16x32_bf16 v[16:19], v[96:99], v[218:221], v[16:19]
	v_mfma_f32_16x16x32_bf16 v[12:15], v[100:103], v[214:217], v[12:15]
	v_mfma_f32_16x16x32_bf16 v[12:15], v[104:107], v[218:221], v[12:15]
	s_barrier
; #define PG8_STAGE(bufoff, gbase, voff) do { _Pragma("unroll") for (int _i = 0; _i < 2; ++_i) \
;         __builtin_amdgcn_global_load_lds((const unsigned*)((const char*)(gbase) + (voff)[_i]), (PG8_LAS unsigned*)(lds + (bufoff) + ldsw + _i * 8192), 16, 0, 0); } while (0)
; #define PG8_LDA(dst, b, h) do { _Pragma("unroll") for (int m = 0; m < 4; ++m) _Pragma("unroll") for (int k = 0; k < 2; ++k) dst[m][k] = *(const PG8_LAS bf16x8*)(lds + PG8_SA(b, h) + aoff + m * 2048 + k * 1024); } while (0)
; #define PG8_LDB(dst, b, h) do { _Pragma("unroll") for (int n = 0; n < 2; ++n) _Pragma("unroll") for (int k = 0; k < 2; ++k) dst[n][k] = *(const PG8_LAS bf16x8*)(lds + PG8_SB(b, h) + boff + n * 2048 + k * 1024); } while (0)
; #define PG8_MMA(ai, bj, At, Bt) do { __builtin_amdgcn_s_setprio(1); _Pragma("unroll") for (int m = 0; m < 4; ++m) _Pragma("unroll") for (int n = 0; n < 2; ++n) _Pragma("unroll") for (int k = 0; k < 2; ++k) \
;         acc[ai][bj][m][n] = __builtin_amdgcn_mfma_f32_16x16x32_bf16(Bt[n][k], At[m][k], acc[ai][bj][m][n], 0, 0, 0); __builtin_amdgcn_s_setprio(0); } while (0)
; #define PG8_WAIT_V(n) asm volatile("s_waitcnt vmcnt(" #n ")" ::: "memory")
; #define PG8_WAIT_L(n) asm volatile("s_waitcnt lgkmcnt(" #n ")" ::: "memory")
; #define PG8_BAR __builtin_amdgcn_s_barrier()
; #define PG8_SCHED __builtin_amdgcn_sched_barrier(0)
; template <class Epi, class Sched, bool ALIGN_EPI = true>
; __device__ __forceinline__ void gemm_phase(PG8_LAS unsigned char* lds, const Gemm g, const Sched& S, const Epi& E, const int tid) {
;     ...
;             PG8_LDB(B0, 1, 0); PG8_LDB(B1, 1, 1); PG8_SCHED; PG8_LDA(At, 1, 0); PG8_STAGE(PG8_SA(0, 1), a2 + hstepA, voffA);
;             PG8_WAIT_V(8); PG8_WAIT_L(0); PG8_BAR; PG8_MMA(0, 0, At, B0); PG8_MMA(0, 1, At, B1); PG8_BAR; PG8_SCHED;
;             PG8_LDA(At, 1, 1); PG8_STAGE(PG8_SB(1, 0), b3, voffB); PG8_STAGE(PG8_SB(1, 1), b3 + hstepB, voffB); PG8_STAGE(PG8_SA(1, 0), a3, voffA);
;             PG8_WAIT_V(8); PG8_WAIT_L(0); PG8_BAR; PG8_MMA(1, 0, At, B0); PG8_MMA(1, 1, At, B1); PG8_BAR; PG8_SCHED;
;         }
;         if constexpr (ALIGN_EPI) { if (wr == 0) PG8_BAR; }
;         E(acc, cur, wr, wc, fr, fq); S.done(cur);
	s_add_i32 s15, 0, 0x18000
	s_add_i32 s16, 0, 0x1c000
	v_add_u32_e32 v88, s15, v193
	v_add_u32_e32 v104, s16, v193
	ds_read_b128 v[72:75], v88
	ds_read_b128 v[76:79], v88 offset:1024
	ds_read_b128 v[84:87], v88 offset:2048
	ds_read_b128 v[88:91], v88 offset:3072
	ds_read_b128 v[92:95], v104
	ds_read_b128 v[96:99], v104 offset:1024
	ds_read_b128 v[100:103], v104 offset:2048
	ds_read_b128 v[104:107], v104 offset:3072
	s_add_u32 s78, s78, 0x80000
	s_addc_u32 s79, s79, 0
	s_mov_b32 m0, s88
	ds_read_b128 v[164:167], v200 offset:32768
	ds_read_b128 v[168:171], v200 offset:33792
	ds_read_b128 v[172:175], v200 offset:34816
	ds_read_b128 v[176:179], v200 offset:35840
	ds_read_b128 v[202:205], v200 offset:36864
	ds_read_b128 v[210:213], v200 offset:37888
	ds_read_b128 v[214:217], v200 offset:38912
	ds_read_b128 v[218:221], v200 offset:39936
	global_load_lds_dwordx4 v180, s[78:79]
	s_mov_b32 m0, s89
	s_nop 0
	global_load_lds_dwordx4 v182, s[78:79]
	s_waitcnt vmcnt(8)
	s_waitcnt lgkmcnt(0)
	s_barrier
	s_waitcnt lgkmcnt(0)
	v_mfma_f32_16x16x32_bf16 v[160:163], v[72:75], v[164:167], v[160:163]
	v_mfma_f32_16x16x32_bf16 v[160:163], v[76:79], v[168:171], v[160:163]
	v_mfma_f32_16x16x32_bf16 v[156:159], v[84:87], v[164:167], v[156:159]
	v_mfma_f32_16x16x32_bf16 v[156:159], v[88:91], v[168:171], v[156:159]
	v_mfma_f32_16x16x32_bf16 v[144:147], v[72:75], v[172:175], v[144:147]
	v_mfma_f32_16x16x32_bf16 v[144:147], v[76:79], v[176:179], v[144:147]
	v_mfma_f32_16x16x32_bf16 v[140:143], v[84:87], v[172:175], v[140:143]
	v_mfma_f32_16x16x32_bf16 v[140:143], v[88:91], v[176:179], v[140:143]
	v_mfma_f32_16x16x32_bf16 v[128:131], v[72:75], v[202:205], v[128:131]
	v_mfma_f32_16x16x32_bf16 v[128:131], v[76:79], v[210:213], v[128:131]
	v_mfma_f32_16x16x32_bf16 v[124:127], v[84:87], v[202:205], v[124:127]
	v_mfma_f32_16x16x32_bf16 v[124:127], v[88:91], v[210:213], v[124:127]
	v_mfma_f32_16x16x32_bf16 v[80:83], v[72:75], v[214:217], v[80:83]
	v_mfma_f32_16x16x32_bf16 v[80:83], v[76:79], v[218:221], v[80:83]
	v_mfma_f32_16x16x32_bf16 v[68:71], v[84:87], v[214:217], v[68:71]
	v_mfma_f32_16x16x32_bf16 v[68:71], v[88:91], v[218:221], v[68:71]
	v_mfma_f32_16x16x32_bf16 v[152:155], v[92:95], v[164:167], v[152:155]
	v_mfma_f32_16x16x32_bf16 v[152:155], v[96:99], v[168:171], v[152:155]
	v_mfma_f32_16x16x32_bf16 v[148:151], v[100:103], v[164:167], v[148:151]
	v_mfma_f32_16x16x32_bf16 v[148:151], v[104:107], v[168:171], v[148:151]
	v_mfma_f32_16x16x32_bf16 v[136:139], v[92:95], v[172:175], v[136:139]
	v_mfma_f32_16x16x32_bf16 v[136:139], v[96:99], v[176:179], v[136:139]
	v_mfma_f32_16x16x32_bf16 v[132:135], v[100:103], v[172:175], v[132:135]
	v_mfma_f32_16x16x32_bf16 v[132:135], v[104:107], v[176:179], v[132:135]
	v_mfma_f32_16x16x32_bf16 v[120:123], v[92:95], v[202:205], v[120:123]
	v_mfma_f32_16x16x32_bf16 v[120:123], v[96:99], v[210:213], v[120:123]
	v_mfma_f32_16x16x32_bf16 v[116:119], v[100:103], v[202:205], v[116:119]
	v_mfma_f32_16x16x32_bf16 v[116:119], v[104:107], v[210:213], v[116:119]
	v_mfma_f32_16x16x32_bf16 v[112:115], v[92:95], v[214:217], v[112:115]
	v_mfma_f32_16x16x32_bf16 v[112:115], v[96:99], v[218:221], v[112:115]
	v_mfma_f32_16x16x32_bf16 v[108:111], v[100:103], v[214:217], v[108:111]
	v_mfma_f32_16x16x32_bf16 v[108:111], v[104:107], v[218:221], v[108:111]
	s_barrier
	s_add_i32 s15, s15, s85
	s_mov_b32 m0, s15
	ds_read_b128 v[164:167], v200 offset:49152
	ds_read_b128 v[168:171], v200 offset:50176
	ds_read_b128 v[172:175], v200 offset:51200
	ds_read_b128 v[176:179], v200 offset:52224
	ds_read_b128 v[202:205], v200 offset:53248
	ds_read_b128 v[210:213], v200 offset:54272
	ds_read_b128 v[214:217], v200 offset:55296
	ds_read_b128 v[218:221], v200 offset:56320
	s_add_u32 s98, s76, 0x80
	s_addc_u32 s99, s77, 0
	global_load_lds_dwordx4 v2, s[98:99]
	s_add_i32 m0, s15, 0x2000
	s_add_u32 s76, s76, 0x80080
	s_addc_u32 s77, s77, 0
	s_add_i32 s15, s16, s85
	global_load_lds_dwordx4 v184, s[98:99]
	s_mov_b32 m0, s15
	s_nop 0
	global_load_lds_dwordx4 v2, s[76:77]
	s_add_i32 m0, s15, 0x2000
	s_nop 0
	global_load_lds_dwordx4 v184, s[76:77]
	s_mov_b32 m0, s92
	s_nop 0
	s_add_u32 s98, s78, 0xfff80080
	s_addc_u32 s99, s79, -1
	global_load_lds_dwordx4 v180, s[98:99]
	s_mov_b32 m0, s93
	s_nop 0
	global_load_lds_dwordx4 v182, s[98:99]
	s_waitcnt vmcnt(8)
	s_waitcnt lgkmcnt(0)
	s_barrier
	s_waitcnt lgkmcnt(0)
	v_mfma_f32_16x16x32_bf16 v[64:67], v[72:75], v[164:167], v[64:67]
	v_mfma_f32_16x16x32_bf16 v[64:67], v[76:79], v[168:171], v[64:67]
	v_mfma_f32_16x16x32_bf16 v[60:63], v[84:87], v[164:167], v[60:63]
	v_mfma_f32_16x16x32_bf16 v[60:63], v[88:91], v[168:171], v[60:63]
	v_mfma_f32_16x16x32_bf16 v[48:51], v[72:75], v[172:175], v[48:51]
	v_mfma_f32_16x16x32_bf16 v[48:51], v[76:79], v[176:179], v[48:51]
	v_mfma_f32_16x16x32_bf16 v[44:47], v[84:87], v[172:175], v[44:47]
	v_mfma_f32_16x16x32_bf16 v[44:47], v[88:91], v[176:179], v[44:47]
	v_mfma_f32_16x16x32_bf16 v[32:35], v[72:75], v[202:205], v[32:35]
	v_mfma_f32_16x16x32_bf16 v[32:35], v[76:79], v[210:213], v[32:35]
	v_mfma_f32_16x16x32_bf16 v[28:31], v[84:87], v[202:205], v[28:31]
	v_mfma_f32_16x16x32_bf16 v[28:31], v[88:91], v[210:213], v[28:31]
	v_mfma_f32_16x16x32_bf16 v[8:11], v[72:75], v[214:217], v[8:11]
	v_mfma_f32_16x16x32_bf16 v[8:11], v[76:79], v[218:221], v[8:11]
	v_mfma_f32_16x16x32_bf16 v[4:7], v[84:87], v[214:217], v[4:7]
	v_mfma_f32_16x16x32_bf16 v[4:7], v[88:91], v[218:221], v[4:7]
	v_mfma_f32_16x16x32_bf16 v[56:59], v[92:95], v[164:167], v[56:59]
	v_mfma_f32_16x16x32_bf16 v[56:59], v[96:99], v[168:171], v[56:59]
	v_mfma_f32_16x16x32_bf16 v[52:55], v[100:103], v[164:167], v[52:55]
	v_mfma_f32_16x16x32_bf16 v[52:55], v[104:107], v[168:171], v[52:55]
	v_mfma_f32_16x16x32_bf16 v[40:43], v[92:95], v[172:175], v[40:43]
	v_mfma_f32_16x16x32_bf16 v[40:43], v[96:99], v[176:179], v[40:43]
	v_mfma_f32_16x16x32_bf16 v[36:39], v[100:103], v[172:175], v[36:39]
	v_mfma_f32_16x16x32_bf16 v[36:39], v[104:107], v[176:179], v[36:39]
	v_mfma_f32_16x16x32_bf16 v[24:27], v[92:95], v[202:205], v[24:27]
	v_mfma_f32_16x16x32_bf16 v[24:27], v[96:99], v[210:213], v[24:27]
	v_mfma_f32_16x16x32_bf16 v[20:23], v[100:103], v[202:205], v[20:23]
	v_mfma_f32_16x16x32_bf16 v[20:23], v[104:107], v[210:213], v[20:23]
	v_mfma_f32_16x16x32_bf16 v[16:19], v[92:95], v[214:217], v[16:19]
	v_mfma_f32_16x16x32_bf16 v[16:19], v[96:99], v[218:221], v[16:19]
	v_mfma_f32_16x16x32_bf16 v[12:15], v[100:103], v[214:217], v[12:15]
	v_mfma_f32_16x16x32_bf16 v[12:15], v[104:107], v[218:221], v[12:15]
	s_barrier
	s_add_i32 s21, s21, 2
	s_add_u32 s74, s74, 0x100
	s_addc_u32 s75, s75, 0
	s_add_u32 s19, s19, 0x100
	s_addc_u32 s20, s20, 0
	s_cmp_gt_u32 s21, 29
	s_cbranch_scc0 .LBB0_1238
	s_and_b64 vcc, exec, s[56:57]
	s_cbranch_vccnz .LBB0_1264
	s_and_saveexec_b64 s[18:19], s[38:39]
	s_cbranch_execnz .LBB0_1265

; #define PG8_STAGE(bufoff, gbase, voff) do { _Pragma("unroll") for (int _i = 0; _i < 2; ++_i) \
;         __builtin_amdgcn_global_load_lds((const unsigned*)((const char*)(gbase) + (voff)[_i]), (PG8_LAS unsigned*)(lds + (bufoff) + ldsw + _i * 8192), 16, 0, 0); } while (0)
; #define PG8_LDA(dst, b, h) do { _Pragma("unroll") for (int m = 0; m < 4; ++m) _Pragma("unroll") for (int k = 0; k < 2; ++k) dst[m][k] = *(const PG8_LAS bf16x8*)(lds + PG8_SA(b, h) + aoff + m * 2048 + k * 1024); } while (0)
; #define PG8_LDB(dst, b, h) do { _Pragma("unroll") for (int n = 0; n < 2; ++n) _Pragma("unroll") for (int k = 0; k < 2; ++k) dst[n][k] = *(const PG8_LAS bf16x8*)(lds + PG8_SB(b, h) + boff + n * 2048 + k * 1024); } while (0)
; #define PG8_MMA(ai, bj, At, Bt) do { __builtin_amdgcn_s_setprio(1); _Pragma("unroll") for (int m = 0; m < 4; ++m) _Pragma("unroll") for (int n = 0; n < 2; ++n) _Pragma("unroll") for (int k = 0; k < 2; ++k) \
;         acc[ai][bj][m][n] = __builtin_amdgcn_mfma_f32_16x16x32_bf16(Bt[n][k], At[m][k], acc[ai][bj][m][n], 0, 0, 0); __builtin_amdgcn_s_setprio(0); } while (0)
; #define PG8_WAIT_V(n) asm volatile("s_waitcnt vmcnt(" #n ")" ::: "memory")
; #define PG8_WAIT_L(n) asm volatile("s_waitcnt lgkmcnt(" #n ")" ::: "memory")
; #define PG8_BAR __builtin_amdgcn_s_barrier()
; template <class Epi, class Sched, bool ALIGN_EPI = true>
; __device__ __forceinline__ void gemm_phase(PG8_LAS unsigned char* lds, const Gemm g, const Sched& S, const Epi& E, const int tid) {
;     ...
;             const bool last = (t == nt - 2);
;             const char* a1 = cA + (size_t)(t + 1) * kstep;
;             const char* a2 = last ? nA : cA + (size_t)(t + 2) * kstep; const char* b2 = last ? nB : cB + (size_t)(t + 2) * kstep;
;             const char* a3 = a2 + kstep; const char* b3 = b2 + kstep;
;             if (last && has_next) S.a_ready(nxt);
;             PG8_LDB(B0, 0, 0); PG8_LDB(B1, 0, 1); PG8_SCHED; PG8_LDA(At, 0, 0); PG8_STAGE(PG8_SA(1, 1), a1 + hstepA, voffA);
;             PG8_WAIT_V(8); PG8_WAIT_L(0); PG8_BAR; PG8_MMA(0, 0, At, B0); PG8_MMA(0, 1, At, B1); PG8_BAR; PG8_SCHED;
;             PG8_LDA(At, 0, 1); PG8_STAGE(PG8_SB(0, 0), b2, voffB); PG8_STAGE(PG8_SB(0, 1), b2 + hstepB, voffB); PG8_STAGE(PG8_SA(0, 0), a2, voffA);
;             PG8_WAIT_V(8); PG8_WAIT_L(0); PG8_BAR; PG8_MMA(1, 0, At, B0); PG8_MMA(1, 1, At, B1); PG8_BAR; PG8_SCHED;
.LBB0_1414:
	s_add_i32 s70, s12, 2
	s_add_u32 s10, s0, 0x100
	s_addc_u32 s11, s1, 0
	s_add_i32 s15, 0, 0x10000
	s_cmp_eq_u32 s45, s12
	s_cselect_b32 s23, s47, s11
	s_cselect_b32 s22, s46, s10
	s_cselect_b32 s13, s49, s69
	s_cselect_b32 s12, s48, s68
	s_add_i32 s16, 0, 0x14000
	v_add_u32_e32 v72, s15, v251
	v_add_u32_e32 v128, s16, v251
	ds_read_b128 v[56:59], v72
	ds_read_b128 v[60:63], v72 offset:1024
	ds_read_b128 v[68:71], v72 offset:2048
	ds_read_b128 v[72:75], v72 offset:3072
	ds_read_b128 v[92:95], v128
	ds_read_b128 v[104:107], v128 offset:1024
	ds_read_b128 v[116:119], v128 offset:2048
	ds_read_b128 v[128:131], v128 offset:3072
	s_add_i32 m0, s52, 0xc000
	ds_read_b128 v[140:143], v252
	ds_read_b128 v[152:155], v252 offset:1024
	ds_read_b128 v[156:159], v252 offset:2048
	ds_read_b128 v[160:163], v252 offset:3072
	ds_read_b128 v[172:175], v252 offset:4096
	ds_read_b128 v[184:187], v252 offset:5120
	ds_read_b128 v[188:191], v252 offset:6144
	ds_read_b128 v[192:195], v252 offset:7168
	global_load_lds_dwordx4 v216, s[0:1]
	s_add_i32 m0, s52, 0xe000
	s_nop 0
	global_load_lds_dwordx4 v218, s[0:1]
	s_waitcnt vmcnt(8)
	s_waitcnt lgkmcnt(0)
	s_barrier
	s_waitcnt lgkmcnt(0)
	v_mfma_f32_16x16x32_bf16 v[180:183], v[56:59], v[140:143], v[180:183]
	v_mfma_f32_16x16x32_bf16 v[180:183], v[60:63], v[152:155], v[180:183]
	v_mfma_f32_16x16x32_bf16 v[176:179], v[68:71], v[140:143], v[176:179]
	v_mfma_f32_16x16x32_bf16 v[176:179], v[72:75], v[152:155], v[176:179]
	v_mfma_f32_16x16x32_bf16 v[148:151], v[56:59], v[156:159], v[148:151]
	v_mfma_f32_16x16x32_bf16 v[148:151], v[60:63], v[160:163], v[148:151]
	v_mfma_f32_16x16x32_bf16 v[144:147], v[68:71], v[156:159], v[144:147]
	v_mfma_f32_16x16x32_bf16 v[144:147], v[72:75], v[160:163], v[144:147]
	v_mfma_f32_16x16x32_bf16 v[124:127], v[56:59], v[172:175], v[124:127]
	v_mfma_f32_16x16x32_bf16 v[124:127], v[60:63], v[184:187], v[124:127]
	v_mfma_f32_16x16x32_bf16 v[120:123], v[68:71], v[172:175], v[120:123]
	v_mfma_f32_16x16x32_bf16 v[120:123], v[72:75], v[184:187], v[120:123]
	v_mfma_f32_16x16x32_bf16 v[100:103], v[56:59], v[188:191], v[100:103]
	v_mfma_f32_16x16x32_bf16 v[100:103], v[60:63], v[192:195], v[100:103]
	v_mfma_f32_16x16x32_bf16 v[96:99], v[68:71], v[188:191], v[96:99]
	v_mfma_f32_16x16x32_bf16 v[96:99], v[72:75], v[192:195], v[96:99]
	v_mfma_f32_16x16x32_bf16 v[168:171], v[92:95], v[140:143], v[168:171]
	v_mfma_f32_16x16x32_bf16 v[136:139], v[92:95], v[156:159], v[136:139]
	v_mfma_f32_16x16x32_bf16 v[132:135], v[116:119], v[156:159], v[132:135]
	v_mfma_f32_16x16x32_bf16 v[112:115], v[92:95], v[172:175], v[112:115]
	v_mfma_f32_16x16x32_bf16 v[108:111], v[116:119], v[172:175], v[108:111]
	v_mfma_f32_16x16x32_bf16 v[88:91], v[92:95], v[188:191], v[88:91]
	v_mfma_f32_16x16x32_bf16 v[84:87], v[116:119], v[188:191], v[84:87]
	v_mfma_f32_16x16x32_bf16 v[168:171], v[104:107], v[152:155], v[168:171]
	v_mfma_f32_16x16x32_bf16 v[140:143], v[116:119], v[140:143], v[164:167]
	v_mfma_f32_16x16x32_bf16 v[136:139], v[104:107], v[160:163], v[136:139]
	v_mfma_f32_16x16x32_bf16 v[132:135], v[128:131], v[160:163], v[132:135]
	v_mfma_f32_16x16x32_bf16 v[112:115], v[104:107], v[184:187], v[112:115]
	v_mfma_f32_16x16x32_bf16 v[108:111], v[128:131], v[184:187], v[108:111]
	v_mfma_f32_16x16x32_bf16 v[88:91], v[104:107], v[192:195], v[88:91]
	v_mfma_f32_16x16x32_bf16 v[84:87], v[128:131], v[192:195], v[84:87]
	v_mfma_f32_16x16x32_bf16 v[140:143], v[128:131], v[152:155], v[140:143]
	s_barrier
	s_add_i32 s0, s15, s51
	s_mov_b32 m0, s0
	ds_read_b128 v[152:155], v252 offset:16384
	ds_read_b128 v[156:159], v252 offset:17408
	ds_read_b128 v[160:163], v252 offset:18432
	ds_read_b128 v[164:167], v252 offset:19456
	ds_read_b128 v[172:175], v252 offset:20480
	ds_read_b128 v[184:187], v252 offset:21504
	ds_read_b128 v[188:191], v252 offset:22528
	ds_read_b128 v[192:195], v252 offset:23552
	global_load_lds_dwordx4 v2, s[12:13]
	s_add_i32 m0, s0, 0x2000
	s_add_u32 s0, s12, 0x168000
	s_addc_u32 s1, s13, 0
	s_add_i32 s15, s16, s51
	global_load_lds_dwordx4 v214, s[12:13]
	s_mov_b32 m0, s15
	s_nop 0
	global_load_lds_dwordx4 v2, s[0:1]
	s_add_i32 m0, s15, 0x2000
	s_nop 0
	global_load_lds_dwordx4 v214, s[0:1]
	s_mov_b32 m0, s52
	s_nop 0
	global_load_lds_dwordx4 v210, s[22:23]
	s_mov_b32 m0, s53
	s_nop 0
	global_load_lds_dwordx4 v212, s[22:23]
	s_waitcnt vmcnt(8)
	s_waitcnt lgkmcnt(0)
	s_barrier
	s_waitcnt lgkmcnt(0)
	v_mfma_f32_16x16x32_bf16 v[80:83], v[56:59], v[152:155], v[80:83]
	v_mfma_f32_16x16x32_bf16 v[80:83], v[60:63], v[156:159], v[80:83]
	v_mfma_f32_16x16x32_bf16 v[76:79], v[68:71], v[152:155], v[76:79]
	v_mfma_f32_16x16x32_bf16 v[76:79], v[72:75], v[156:159], v[76:79]
	v_mfma_f32_16x16x32_bf16 v[48:51], v[56:59], v[160:163], v[48:51]
	v_mfma_f32_16x16x32_bf16 v[48:51], v[60:63], v[164:167], v[48:51]
	v_mfma_f32_16x16x32_bf16 v[44:47], v[68:71], v[160:163], v[44:47]
	v_mfma_f32_16x16x32_bf16 v[44:47], v[72:75], v[164:167], v[44:47]
	v_mfma_f32_16x16x32_bf16 v[32:35], v[56:59], v[172:175], v[32:35]
	v_mfma_f32_16x16x32_bf16 v[32:35], v[60:63], v[184:187], v[32:35]
	v_mfma_f32_16x16x32_bf16 v[28:31], v[68:71], v[172:175], v[28:31]
	v_mfma_f32_16x16x32_bf16 v[28:31], v[72:75], v[184:187], v[28:31]
	v_mfma_f32_16x16x32_bf16 v[16:19], v[56:59], v[188:191], v[16:19]
	v_mfma_f32_16x16x32_bf16 v[16:19], v[60:63], v[192:195], v[16:19]
	v_mfma_f32_16x16x32_bf16 v[12:15], v[68:71], v[188:191], v[12:15]
	v_mfma_f32_16x16x32_bf16 v[12:15], v[72:75], v[192:195], v[12:15]
	v_mfma_f32_16x16x32_bf16 v[52:55], v[116:119], v[152:155], v[52:55]
	v_mfma_f32_16x16x32_bf16 v[40:43], v[92:95], v[160:163], v[40:43]
	v_mfma_f32_16x16x32_bf16 v[36:39], v[116:119], v[160:163], v[36:39]
	v_mfma_f32_16x16x32_bf16 v[24:27], v[92:95], v[172:175], v[24:27]
	v_mfma_f32_16x16x32_bf16 v[20:23], v[116:119], v[172:175], v[20:23]
	v_mfma_f32_16x16x32_bf16 v[8:11], v[92:95], v[188:191], v[8:11]
	v_mfma_f32_16x16x32_bf16 v[4:7], v[116:119], v[188:191], v[4:7]
	v_mfma_f32_16x16x32_bf16 v[56:59], v[92:95], v[152:155], v[64:67]
	v_mfma_f32_16x16x32_bf16 v[52:55], v[128:131], v[156:159], v[52:55]
	v_mfma_f32_16x16x32_bf16 v[40:43], v[104:107], v[164:167], v[40:43]
	v_mfma_f32_16x16x32_bf16 v[36:39], v[128:131], v[164:167], v[36:39]
	v_mfma_f32_16x16x32_bf16 v[24:27], v[104:107], v[184:187], v[24:27]
	v_mfma_f32_16x16x32_bf16 v[20:23], v[128:131], v[184:187], v[20:23]
	v_mfma_f32_16x16x32_bf16 v[8:11], v[104:107], v[192:195], v[8:11]
	v_mfma_f32_16x16x32_bf16 v[4:7], v[128:131], v[192:195], v[4:7]
	v_mfma_f32_16x16x32_bf16 v[56:59], v[104:107], v[156:159], v[56:59]
	s_barrier
; #define PG8_STAGE(bufoff, gbase, voff) do { _Pragma("unroll") for (int _i = 0; _i < 2; ++_i) \
;         __builtin_amdgcn_global_load_lds((const unsigned*)((const char*)(gbase) + (voff)[_i]), (PG8_LAS unsigned*)(lds + (bufoff) + ldsw + _i * 8192), 16, 0, 0); } while (0)
; #define PG8_LDA(dst, b, h) do { _Pragma("unroll") for (int m = 0; m < 4; ++m) _Pragma("unroll") for (int k = 0; k < 2; ++k) dst[m][k] = *(const PG8_LAS bf16x8*)(lds + PG8_SA(b, h) + aoff + m * 2048 + k * 1024); } while (0)
; #define PG8_LDB(dst, b, h) do { _Pragma("unroll") for (int n = 0; n < 2; ++n) _Pragma("unroll") for (int k = 0; k < 2; ++k) dst[n][k] = *(const PG8_LAS bf16x8*)(lds + PG8_SB(b, h) + boff + n * 2048 + k * 1024); } while (0)
; #define PG8_MMA(ai, bj, At, Bt) do { __builtin_amdgcn_s_setprio(1); _Pragma("unroll") for (int m = 0; m < 4; ++m) _Pragma("unroll") for (int n = 0; n < 2; ++n) _Pragma("unroll") for (int k = 0; k < 2; ++k) \
;         acc[ai][bj][m][n] = __builtin_amdgcn_mfma_f32_16x16x32_bf16(Bt[n][k], At[m][k], acc[ai][bj][m][n], 0, 0, 0); __builtin_amdgcn_s_setprio(0); } while (0)
; #define PG8_WAIT_V(n) asm volatile("s_waitcnt vmcnt(" #n ")" ::: "memory")
; #define PG8_WAIT_L(n) asm volatile("s_waitcnt lgkmcnt(" #n ")" ::: "memory")
; #define PG8_BAR __builtin_amdgcn_s_barrier()
; #define PG8_SCHED __builtin_amdgcn_sched_barrier(0)
; template <class Epi, class Sched, bool ALIGN_EPI = true>
; __device__ __forceinline__ void gemm_phase(PG8_LAS unsigned char* lds, const Gemm g, const Sched& S, const Epi& E, const int tid) {
;     ...
;             PG8_LDB(B0, 1, 0); PG8_LDB(B1, 1, 1); PG8_SCHED; PG8_LDA(At, 1, 0); PG8_STAGE(PG8_SA(0, 1), a2 + hstepA, voffA);
;             PG8_WAIT_V(8); PG8_WAIT_L(0); PG8_BAR; PG8_MMA(0, 0, At, B0); PG8_MMA(0, 1, At, B1); PG8_BAR; PG8_SCHED;
;             PG8_LDA(At, 1, 1); PG8_STAGE(PG8_SB(1, 0), b3, voffB); PG8_STAGE(PG8_SB(1, 1), b3 + hstepB, voffB); PG8_STAGE(PG8_SA(1, 0), a3, voffA);
;             PG8_WAIT_V(8); PG8_WAIT_L(0); PG8_BAR; PG8_MMA(1, 0, At, B0); PG8_MMA(1, 1, At, B1); PG8_BAR; PG8_SCHED;
;         }
;         if constexpr (ALIGN_EPI) { if (wr == 0) PG8_BAR; }
	s_add_i32 s15, 0, 0x18000
	s_add_i32 s16, 0, 0x1c000
	v_add_u32_e32 v72, s15, v251
	v_add_u32_e32 v128, s16, v251
	ds_read_b128 v[60:63], v72
	ds_read_b128 v[64:67], v72 offset:1024
	ds_read_b128 v[68:71], v72 offset:2048
	ds_read_b128 v[72:75], v72 offset:3072
	ds_read_b128 v[92:95], v128
	ds_read_b128 v[104:107], v128 offset:1024
	ds_read_b128 v[116:119], v128 offset:2048
	ds_read_b128 v[128:131], v128 offset:3072
	s_add_u32 s0, s22, 0x168000
	s_addc_u32 s1, s23, 0
	s_mov_b32 m0, s54
	ds_read_b128 v[152:155], v252 offset:32768
	ds_read_b128 v[156:159], v252 offset:33792
	ds_read_b128 v[160:163], v252 offset:34816
	ds_read_b128 v[172:175], v252 offset:35840
	ds_read_b128 v[184:187], v252 offset:36864
	ds_read_b128 v[188:191], v252 offset:37888
	ds_read_b128 v[192:195], v252 offset:38912
	ds_read_b128 v[196:199], v252 offset:39936
	global_load_lds_dwordx4 v210, s[0:1]
	s_mov_b32 m0, s55
	s_nop 0
	global_load_lds_dwordx4 v212, s[0:1]
	s_waitcnt vmcnt(8)
	s_waitcnt lgkmcnt(0)
	s_barrier
	s_waitcnt lgkmcnt(0)
	v_mfma_f32_16x16x32_bf16 v[164:167], v[60:63], v[152:155], v[180:183]
	v_mfma_f32_16x16x32_bf16 v[180:183], v[64:67], v[156:159], v[164:167]
	v_mfma_f32_16x16x32_bf16 v[164:167], v[68:71], v[152:155], v[176:179]
	v_mfma_f32_16x16x32_bf16 v[148:151], v[60:63], v[160:163], v[148:151]
	v_mfma_f32_16x16x32_bf16 v[144:147], v[68:71], v[160:163], v[144:147]
	v_mfma_f32_16x16x32_bf16 v[124:127], v[60:63], v[184:187], v[124:127]
	v_mfma_f32_16x16x32_bf16 v[120:123], v[68:71], v[184:187], v[120:123]
	v_mfma_f32_16x16x32_bf16 v[100:103], v[60:63], v[192:195], v[100:103]
	v_mfma_f32_16x16x32_bf16 v[96:99], v[68:71], v[192:195], v[96:99]
	v_mfma_f32_16x16x32_bf16 v[176:179], v[72:75], v[156:159], v[164:167]
	v_mfma_f32_16x16x32_bf16 v[148:151], v[64:67], v[172:175], v[148:151]
	v_mfma_f32_16x16x32_bf16 v[144:147], v[72:75], v[172:175], v[144:147]
	v_mfma_f32_16x16x32_bf16 v[124:127], v[64:67], v[188:191], v[124:127]
	v_mfma_f32_16x16x32_bf16 v[120:123], v[72:75], v[188:191], v[120:123]
	v_mfma_f32_16x16x32_bf16 v[100:103], v[64:67], v[196:199], v[100:103]
	v_mfma_f32_16x16x32_bf16 v[96:99], v[72:75], v[196:199], v[96:99]
	v_mfma_f32_16x16x32_bf16 v[164:167], v[92:95], v[152:155], v[168:171]
	v_mfma_f32_16x16x32_bf16 v[140:143], v[116:119], v[152:155], v[140:143]
	v_mfma_f32_16x16x32_bf16 v[136:139], v[92:95], v[160:163], v[136:139]
	v_mfma_f32_16x16x32_bf16 v[132:135], v[116:119], v[160:163], v[132:135]
	v_mfma_f32_16x16x32_bf16 v[112:115], v[92:95], v[184:187], v[112:115]
	v_mfma_f32_16x16x32_bf16 v[108:111], v[116:119], v[184:187], v[108:111]
	v_mfma_f32_16x16x32_bf16 v[88:91], v[92:95], v[192:195], v[88:91]
	v_mfma_f32_16x16x32_bf16 v[84:87], v[116:119], v[192:195], v[84:87]
	v_mfma_f32_16x16x32_bf16 v[168:171], v[104:107], v[156:159], v[164:167]
	v_mfma_f32_16x16x32_bf16 v[164:167], v[128:131], v[156:159], v[140:143]
	v_mfma_f32_16x16x32_bf16 v[136:139], v[104:107], v[172:175], v[136:139]
	v_mfma_f32_16x16x32_bf16 v[132:135], v[128:131], v[172:175], v[132:135]
	v_mfma_f32_16x16x32_bf16 v[112:115], v[104:107], v[188:191], v[112:115]
	v_mfma_f32_16x16x32_bf16 v[108:111], v[128:131], v[188:191], v[108:111]
	v_mfma_f32_16x16x32_bf16 v[88:91], v[104:107], v[196:199], v[88:91]
	v_mfma_f32_16x16x32_bf16 v[84:87], v[128:131], v[196:199], v[84:87]
	s_barrier
	s_add_i32 s0, s15, s51
	s_mov_b32 m0, s0
	ds_read_b128 v[140:143], v252 offset:49152
	ds_read_b128 v[152:155], v252 offset:50176
	ds_read_b128 v[156:159], v252 offset:51200
	ds_read_b128 v[160:163], v252 offset:52224
	ds_read_b128 v[172:175], v252 offset:53248
	ds_read_b128 v[184:187], v252 offset:54272
	ds_read_b128 v[188:191], v252 offset:55296
	ds_read_b128 v[192:195], v252 offset:56320
	s_add_u32 s98, s12, 0x80
	s_addc_u32 s99, s13, 0
	global_load_lds_dwordx4 v2, s[98:99]
	s_add_i32 m0, s0, 0x2000
	s_add_u32 s0, s12, 0x168080
	s_addc_u32 s1, s13, 0
	s_add_i32 s12, s16, s51
	global_load_lds_dwordx4 v214, s[98:99]
	s_mov_b32 m0, s12
	s_nop 0
	global_load_lds_dwordx4 v2, s[0:1]
	s_add_i32 m0, s12, 0x2000
	s_nop 0
	global_load_lds_dwordx4 v214, s[0:1]
	s_mov_b32 m0, s58
	s_nop 0
	s_add_u32 s98, s22, 0x80
	s_addc_u32 s99, s23, 0
	global_load_lds_dwordx4 v210, s[98:99]
	s_mov_b32 m0, s59
	s_nop 0
	global_load_lds_dwordx4 v212, s[98:99]
	s_waitcnt vmcnt(8)
	s_waitcnt lgkmcnt(0)
	s_barrier
	s_waitcnt lgkmcnt(0)
	v_mfma_f32_16x16x32_bf16 v[80:83], v[60:63], v[140:143], v[80:83]
	v_mfma_f32_16x16x32_bf16 v[80:83], v[64:67], v[152:155], v[80:83]
	v_mfma_f32_16x16x32_bf16 v[76:79], v[68:71], v[140:143], v[76:79]
	v_mfma_f32_16x16x32_bf16 v[76:79], v[72:75], v[152:155], v[76:79]
	v_mfma_f32_16x16x32_bf16 v[48:51], v[60:63], v[156:159], v[48:51]
	v_mfma_f32_16x16x32_bf16 v[48:51], v[64:67], v[160:163], v[48:51]
	v_mfma_f32_16x16x32_bf16 v[44:47], v[68:71], v[156:159], v[44:47]
	v_mfma_f32_16x16x32_bf16 v[44:47], v[72:75], v[160:163], v[44:47]
	v_mfma_f32_16x16x32_bf16 v[32:35], v[60:63], v[172:175], v[32:35]
	v_mfma_f32_16x16x32_bf16 v[32:35], v[64:67], v[184:187], v[32:35]
	v_mfma_f32_16x16x32_bf16 v[28:31], v[68:71], v[172:175], v[28:31]
	v_mfma_f32_16x16x32_bf16 v[28:31], v[72:75], v[184:187], v[28:31]
	v_mfma_f32_16x16x32_bf16 v[16:19], v[60:63], v[188:191], v[16:19]
	v_mfma_f32_16x16x32_bf16 v[16:19], v[64:67], v[192:195], v[16:19]
	v_mfma_f32_16x16x32_bf16 v[12:15], v[68:71], v[188:191], v[12:15]
	v_mfma_f32_16x16x32_bf16 v[12:15], v[72:75], v[192:195], v[12:15]
	v_mfma_f32_16x16x32_bf16 v[56:59], v[92:95], v[140:143], v[56:59]
	v_mfma_f32_16x16x32_bf16 v[52:55], v[116:119], v[140:143], v[52:55]
	v_mfma_f32_16x16x32_bf16 v[40:43], v[92:95], v[156:159], v[40:43]
	v_mfma_f32_16x16x32_bf16 v[36:39], v[116:119], v[156:159], v[36:39]
	v_mfma_f32_16x16x32_bf16 v[24:27], v[92:95], v[172:175], v[24:27]
	v_mfma_f32_16x16x32_bf16 v[20:23], v[116:119], v[172:175], v[20:23]
	v_mfma_f32_16x16x32_bf16 v[8:11], v[92:95], v[188:191], v[8:11]
	v_mfma_f32_16x16x32_bf16 v[4:7], v[116:119], v[188:191], v[4:7]
	v_mfma_f32_16x16x32_bf16 v[64:67], v[104:107], v[152:155], v[56:59]
	v_mfma_f32_16x16x32_bf16 v[52:55], v[128:131], v[152:155], v[52:55]
	v_mfma_f32_16x16x32_bf16 v[40:43], v[104:107], v[160:163], v[40:43]
	v_mfma_f32_16x16x32_bf16 v[36:39], v[128:131], v[160:163], v[36:39]
	v_mfma_f32_16x16x32_bf16 v[24:27], v[104:107], v[184:187], v[24:27]
	v_mfma_f32_16x16x32_bf16 v[20:23], v[128:131], v[184:187], v[20:23]
	v_mfma_f32_16x16x32_bf16 v[8:11], v[104:107], v[192:195], v[8:11]
	v_mfma_f32_16x16x32_bf16 v[4:7], v[128:131], v[192:195], v[4:7]
	s_barrier
	s_add_u32 s68, s68, 0x100
	s_addc_u32 s69, s69, 0
	s_cmp_ge_i32 s70, s67
	s_mov_b64 s[0:1], s[10:11]
	s_mov_b32 s12, s70
	s_cbranch_scc0 .LBB0_1414
	s_nop 0
	s_nop 0
	s_nop 0
	s_nop 0
	s_nop 0
	s_nop 0
	s_nop 0
	s_nop 0
	s_nop 0
	s_nop 0
	s_nop 0
	s_nop 0
	s_and_b64 vcc, exec, s[42:43]
	s_cbranch_vccz .LBB0_1417
	s_barrier
